# router affinities published write-through and no L2 write-back at the barriers before phases 6 and 14 (remaining router outputs are covered by the following barrier)
# baseline (speedup 1.0000x reference)
.LBB0_641:
	v_ashrrev_i32_e32 v11, 31, v10
	v_lshlrev_b64 v[34:35], 11, v[10:11]
	v_lshl_add_u64 v[2:3], v[14:15], 0, v[34:35]
	global_load_dwordx2 v[40:41], v[2:3], off
	global_load_dwordx2 v[44:45], v[2:3], off offset:512
	global_load_dwordx2 v[46:47], v[2:3], off offset:1024
	global_load_dwordx2 v[48:49], v[2:3], off offset:1536
	s_waitcnt lgkmcnt(0)
	v_add_u32_e32 v4, 1, v10
	v_ashrrev_i32_e32 v5, 31, v4
	v_lshlrev_b64 v[60:61], 11, v[4:5]
	v_lshl_add_u64 v[2:3], v[14:15], 0, v[60:61]
	global_load_dwordx2 v[56:57], v[2:3], off
	global_load_dwordx2 v[58:59], v[2:3], off offset:512
	global_load_dwordx2 v[62:63], v[2:3], off offset:1024
	global_load_dwordx2 v[70:71], v[2:3], off offset:1536
	v_ashrrev_i32_e32 v32, 12, v10
	v_mul_hi_i32_i24_e32 v7, 0x6000, v32
	v_mul_i32_i24_e32 v6, 0x6000, v32
	s_mov_b64 s[4:5], 0x3000
	v_lshl_add_u64 v[6:7], s[44:45], 0, v[6:7]
	v_lshl_add_u64 v[54:55], v[6:7], 0, s[4:5]
	v_lshl_add_u64 v[42:43], v[6:7], 0, s[20:21]
	v_lshl_add_u64 v[6:7], v[54:55], 0, v[22:23]
	v_lshl_add_u64 v[36:37], v[42:43], 0, v[22:23]
	global_load_dwordx4 v[200:203], v[16:17], off offset:1024
	v_lshl_add_u64 v[236:237], v[42:43], 0, v[24:25]
	global_load_dwordx4 v[204:207], v[236:237], off
	v_lshl_add_u64 v[236:237], v[54:55], 0, v[24:25]
	global_load_dwordx4 v[208:211], v[236:237], off
	global_load_dwordx4 v[212:215], v[16:17], off offset:2048
	v_lshl_add_u64 v[236:237], v[42:43], 0, v[26:27]
	global_load_dwordx4 v[216:219], v[236:237], off
	v_lshl_add_u64 v[236:237], v[54:55], 0, v[26:27]
	global_load_dwordx4 v[220:223], v[236:237], off
	global_load_dwordx4 v[224:227], v[16:17], off offset:3072
	v_lshl_add_u64 v[236:237], v[42:43], 0, v[28:29]
	global_load_dwordx4 v[228:231], v[236:237], off
	v_lshl_add_u64 v[236:237], v[54:55], 0, v[28:29]
	global_load_dwordx4 v[232:235], v[236:237], off
	global_load_dwordx4 v[2:5], v[16:17], off
	s_nop 0
	global_load_dwordx4 v[6:9], v[6:7], off
	s_nop 0
	global_load_dwordx4 v[36:39], v[36:37], off
	v_lshl_add_u64 v[60:61], v[20:21], 0, v[60:61]
	s_waitcnt vmcnt(19)
	v_and_b32_e32 v75, 0xffff0000, v40
	s_waitcnt vmcnt(18)
	v_and_b32_e32 v79, 0xffff0000, v44
	s_waitcnt vmcnt(17)
	v_and_b32_e32 v83, 0xffff0000, v46
	s_waitcnt vmcnt(16)
	v_and_b32_e32 v53, 0xffff0000, v48
	v_lshlrev_b32_e32 v82, 16, v46
	v_lshlrev_b32_e32 v52, 16, v48
	v_mov_b32_e32 v96, v83
	v_mov_b32_e32 v97, v53
	v_lshlrev_b32_e32 v80, 16, v47
	v_lshlrev_b32_e32 v50, 16, v49
	v_mov_b32_e32 v94, v82
	v_mov_b32_e32 v95, v52
	v_pk_mul_f32 v[96:97], v[96:97], v[96:97]
	v_lshlrev_b32_e32 v74, 16, v40
	v_lshlrev_b32_e32 v76, 16, v45
	v_and_b32_e32 v77, 0xffff0000, v45
	v_lshlrev_b32_e32 v78, 16, v44
	v_and_b32_e32 v81, 0xffff0000, v47
	v_and_b32_e32 v51, 0xffff0000, v49
	s_waitcnt vmcnt(15)
	v_and_b32_e32 v45, 0xffff0000, v56
	v_mov_b32_e32 v84, v75
	v_mov_b32_e32 v85, v79
	s_waitcnt vmcnt(14)
	v_lshlrev_b32_e32 v86, 16, v59
	v_and_b32_e32 v87, 0xffff0000, v59
	v_lshlrev_b32_e32 v88, 16, v58
	v_and_b32_e32 v89, 0xffff0000, v58
	v_mov_b32_e32 v58, v80
	v_mov_b32_e32 v59, v50
	v_pk_fma_f32 v[94:95], v[94:95], v[94:95], v[96:97]
	v_lshlrev_b32_e32 v72, 16, v41
	v_and_b32_e32 v73, 0xffff0000, v41
	v_lshlrev_b32_e32 v40, 16, v57
	v_and_b32_e32 v41, 0xffff0000, v57
	v_lshlrev_b32_e32 v44, 16, v56
	v_mov_b32_e32 v56, v74
	v_mov_b32_e32 v57, v78
	s_waitcnt vmcnt(13)
	v_lshlrev_b32_e32 v90, 16, v63
	v_and_b32_e32 v91, 0xffff0000, v63
	v_lshlrev_b32_e32 v92, 16, v62
	v_and_b32_e32 v93, 0xffff0000, v62
	v_mov_b32_e32 v62, v81
	v_mov_b32_e32 v63, v51
	v_pk_mul_f32 v[84:85], v[84:85], v[84:85]
	v_mov_b32_e32 v104, v45
	v_mov_b32_e32 v105, v89
	v_pk_fma_f32 v[58:59], v[58:59], v[58:59], v[94:95]
	v_mov_b32_e32 v46, v72
	v_mov_b32_e32 v47, v76
	v_mov_b32_e32 v102, v44
	v_mov_b32_e32 v103, v88
	v_pk_fma_f32 v[56:57], v[56:57], v[56:57], v[84:85]
	v_pk_mul_f32 v[84:85], v[104:105], v[104:105]
	v_pk_fma_f32 v[58:59], v[62:63], v[62:63], v[58:59]
	s_waitcnt vmcnt(12)
	v_and_b32_e32 v63, 0xffff0000, v70
	v_mov_b32_e32 v48, v73
	v_mov_b32_e32 v49, v77
	v_mov_b32_e32 v98, v40
	v_mov_b32_e32 v99, v86
	v_pk_fma_f32 v[46:47], v[46:47], v[46:47], v[56:57]
	v_pk_fma_f32 v[56:57], v[102:103], v[102:103], v[84:85]
	v_lshlrev_b32_e32 v62, 16, v70
	v_mov_b32_e32 v96, v93
	v_mov_b32_e32 v97, v63
	v_pk_fma_f32 v[46:47], v[48:49], v[48:49], v[46:47]
	v_pk_fma_f32 v[48:49], v[98:99], v[98:99], v[56:57]
	v_lshlrev_b32_e32 v56, 16, v71
	v_mov_b32_e32 v94, v92
	v_mov_b32_e32 v95, v62
	v_pk_mul_f32 v[96:97], v[96:97], v[96:97]
	v_mov_b32_e32 v100, v41
	v_mov_b32_e32 v101, v87
	v_and_b32_e32 v57, 0xffff0000, v71
	v_mov_b32_e32 v70, v90
	v_mov_b32_e32 v71, v56
	v_pk_fma_f32 v[94:95], v[94:95], v[94:95], v[96:97]
	v_pk_fma_f32 v[48:49], v[100:101], v[100:101], v[48:49]
	v_mov_b32_e32 v84, v91
	v_mov_b32_e32 v85, v57
	v_pk_fma_f32 v[70:71], v[70:71], v[70:71], v[94:95]
	s_waitcnt vmcnt(0)
	v_pk_add_f32 v[38:39], v[38:39], 1.0 op_sel_hi:[1,0]
	v_pk_fma_f32 v[70:71], v[84:85], v[84:85], v[70:71]
	v_mov_b32_e32 v84, v48
	v_mov_b32_e32 v85, v46
	v_mov_b32_e32 v46, v49
	v_pk_add_f32 v[46:47], v[84:85], v[46:47]
	v_mov_b32_e32 v48, v70
	v_mov_b32_e32 v49, v58
	v_pk_add_f32 v[46:47], v[46:47], v[48:49]
	v_mov_b32_e32 v58, v71
	v_pk_add_f32 v[46:47], v[46:47], v[58:59]
	ds_bpermute_b32 v49, v1, v47
	ds_bpermute_b32 v48, v1, v46
	v_pk_add_f32 v[70:71], v[36:37], 1.0 op_sel_hi:[1,0]
	v_lshl_add_u64 v[58:59], v[20:21], 0, v[34:35]
	s_waitcnt lgkmcnt(0)
	v_pk_add_f32 v[46:47], v[46:47], v[48:49]
	ds_bpermute_b32 v49, v31, v47
	ds_bpermute_b32 v48, v31, v46
	s_waitcnt lgkmcnt(0)
	v_pk_add_f32 v[46:47], v[46:47], v[48:49]
	ds_bpermute_b32 v49, v64, v47
	ds_bpermute_b32 v48, v64, v46
	s_waitcnt lgkmcnt(0)
	v_pk_add_f32 v[46:47], v[46:47], v[48:49]
	ds_bpermute_b32 v49, v65, v47
	ds_bpermute_b32 v48, v65, v46
	s_waitcnt lgkmcnt(0)
	v_pk_add_f32 v[46:47], v[46:47], v[48:49]
	ds_bpermute_b32 v49, v66, v47
	ds_bpermute_b32 v48, v66, v46
	s_waitcnt lgkmcnt(0)
	v_pk_add_f32 v[46:47], v[46:47], v[48:49]
	ds_bpermute_b32 v49, v67, v47
	ds_bpermute_b32 v48, v67, v46
	s_waitcnt lgkmcnt(0)
	v_pk_add_f32 v[36:37], v[46:47], v[48:49]
	s_nop 0
	v_pk_fma_f32 v[46:47], v[36:37], s[22:23], v[30:31] op_sel_hi:[1,0,0]
	v_lshl_add_u64 v[48:49], v[42:43], 0, v[24:25]
	v_mul_f32_e32 v11, 0x4b800000, v47
	v_cmp_gt_f32_e32 vcc, s24, v47
	s_nop 1
	v_cndmask_b32_e32 v11, v47, v11, vcc
	v_rsq_f32_e32 v11, v11
	s_nop 0
	v_mul_f32_e32 v12, 0x45800000, v11
	v_cndmask_b32_e32 v12, v11, v12, vcc
	v_mul_f32_e32 v11, 0x4b800000, v46
	v_cmp_gt_f32_e32 vcc, s24, v46
	v_pk_mul_f32 v[34:35], v[12:13], v[74:75] op_sel_hi:[0,1]
	v_pk_mul_f32 v[34:35], v[2:3], v[34:35]
	v_cndmask_b32_e32 v11, v46, v11, vcc
	v_rsq_f32_e32 v11, v11
	v_pk_fma_f32 v[36:37], v[70:71], v[34:35], v[6:7]
	v_pk_mul_f32 v[34:35], v[12:13], v[72:73] op_sel_hi:[0,1]
	v_pk_mul_f32 v[34:35], v[4:5], v[34:35]
	v_mul_f32_e32 v33, 0x45800000, v11
	v_cndmask_b32_e32 v114, v11, v33, vcc
	v_pk_mul_f32 v[44:45], v[114:115], v[44:45] op_sel_hi:[0,1]
	v_pk_mul_f32 v[2:3], v[2:3], v[44:45]
	v_pk_fma_f32 v[34:35], v[38:39], v[34:35], v[8:9]
	v_pk_fma_f32 v[6:7], v[70:71], v[2:3], v[6:7]
	v_pk_mul_f32 v[2:3], v[114:115], v[40:41] op_sel_hi:[0,1]
	v_pk_mul_f32 v[2:3], v[4:5], v[2:3]
	v_cvt_pk_bf16_f32 v46, v36, v37
	v_pk_fma_f32 v[2:3], v[38:39], v[2:3], v[8:9]
	v_cvt_pk_bf16_f32 v47, v34, v35
	v_cvt_pk_bf16_f32 v4, v6, v7
	v_cvt_pk_bf16_f32 v5, v2, v3
	global_store_dwordx2 v[58:59], v[46:47], off
	global_store_dwordx2 v[60:61], v[4:5], off
	v_mov_b32_e32 v38, v200
	v_mov_b32_e32 v39, v201
	v_mov_b32_e32 v40, v202
	v_mov_b32_e32 v41, v203
	s_nop 0
	v_mov_b32_e32 v44, v204
	v_mov_b32_e32 v45, v205
	v_mov_b32_e32 v46, v206
	v_mov_b32_e32 v47, v207
	v_lshl_add_u64 v[4:5], v[54:55], 0, v[24:25]
	v_mov_b32_e32 v70, v208
	v_mov_b32_e32 v71, v209
	v_mov_b32_e32 v72, v210
	v_mov_b32_e32 v73, v211
	v_pk_mul_f32 v[4:5], v[12:13], v[78:79] op_sel_hi:[0,1]
	v_pk_mul_f32 v[8:9], v[12:13], v[76:77] op_sel_hi:[0,1]
	v_pk_mul_f32 v[74:75], v[114:115], v[88:89] op_sel_hi:[0,1]
	v_pk_mul_f32 v[76:77], v[114:115], v[86:87] op_sel_hi:[0,1]
	v_lshl_add_u64 v[48:49], v[42:43], 0, v[26:27]
	v_lshl_add_u64 v[78:79], v[42:43], 0, v[28:29]
	v_pk_mul_f32 v[42:43], v[12:13], v[82:83] op_sel_hi:[0,1]
	v_pk_mul_f32 v[82:83], v[114:115], v[90:91] op_sel_hi:[0,1]
	v_pk_mul_f32 v[52:53], v[12:13], v[52:53] op_sel_hi:[0,1]
	v_pk_mul_f32 v[50:51], v[12:13], v[50:51] op_sel_hi:[0,1]
	v_pk_mul_f32 v[56:57], v[114:115], v[56:57] op_sel_hi:[0,1]
	v_pk_mul_f32 v[4:5], v[38:39], v[4:5]
	v_pk_add_f32 v[44:45], v[44:45], 1.0 op_sel_hi:[1,0]
	v_pk_mul_f32 v[8:9], v[40:41], v[8:9]
	v_pk_add_f32 v[46:47], v[46:47], 1.0 op_sel_hi:[1,0]
	v_pk_mul_f32 v[74:75], v[38:39], v[74:75]
	v_pk_mul_f32 v[76:77], v[40:41], v[76:77]
	v_pk_fma_f32 v[40:41], v[4:5], v[44:45], v[70:71]
	v_pk_fma_f32 v[38:39], v[8:9], v[46:47], v[72:73]
	v_pk_fma_f32 v[8:9], v[44:45], v[74:75], v[70:71]
	v_pk_fma_f32 v[4:5], v[46:47], v[76:77], v[72:73]
	v_cvt_pk_bf16_f32 v44, v40, v41
	v_cvt_pk_bf16_f32 v45, v38, v39
	v_cvt_pk_bf16_f32 v46, v8, v9
	v_cvt_pk_bf16_f32 v47, v4, v5
	global_store_dwordx2 v[58:59], v[44:45], off offset:512
	global_store_dwordx2 v[60:61], v[46:47], off offset:512
	v_mov_b32_e32 v44, v212
	v_mov_b32_e32 v45, v213
	v_mov_b32_e32 v46, v214
	v_mov_b32_e32 v47, v215
	s_nop 0
	v_mov_b32_e32 v70, v216
	v_mov_b32_e32 v71, v217
	v_mov_b32_e32 v72, v218
	v_mov_b32_e32 v73, v219
	v_lshl_add_u64 v[48:49], v[54:55], 0, v[26:27]
	v_mov_b32_e32 v74, v220
	v_mov_b32_e32 v75, v221
	v_mov_b32_e32 v76, v222
	v_mov_b32_e32 v77, v223
	v_pk_mul_f32 v[48:49], v[12:13], v[80:81] op_sel_hi:[0,1]
	v_pk_mul_f32 v[80:81], v[114:115], v[92:93] op_sel_hi:[0,1]
	v_lshl_add_u64 v[54:55], v[54:55], 0, v[28:29]
	v_pk_mul_f32 v[42:43], v[42:43], v[44:45]
	v_pk_add_f32 v[70:71], v[70:71], 1.0 op_sel_hi:[1,0]
	v_pk_mul_f32 v[84:85], v[48:49], v[46:47]
	v_pk_add_f32 v[72:73], v[72:73], 1.0 op_sel_hi:[1,0]
	v_pk_mul_f32 v[44:45], v[80:81], v[44:45]
	v_pk_mul_f32 v[80:81], v[82:83], v[46:47]
	v_pk_fma_f32 v[48:49], v[42:43], v[70:71], v[74:75]
	v_pk_fma_f32 v[46:47], v[84:85], v[72:73], v[76:77]
	v_pk_fma_f32 v[44:45], v[44:45], v[70:71], v[74:75]
	v_pk_fma_f32 v[42:43], v[80:81], v[72:73], v[76:77]
	v_cvt_pk_bf16_f32 v70, v48, v49
	v_cvt_pk_bf16_f32 v71, v46, v47
	v_cvt_pk_bf16_f32 v72, v44, v45
	v_cvt_pk_bf16_f32 v73, v42, v43
	global_store_dwordx2 v[58:59], v[70:71], off offset:1024
	global_store_dwordx2 v[60:61], v[72:73], off offset:1024
	v_mov_b32_e32 v70, v224
	v_mov_b32_e32 v71, v225
	v_mov_b32_e32 v72, v226
	v_mov_b32_e32 v73, v227
	s_nop 0
	v_mov_b32_e32 v74, v228
	v_mov_b32_e32 v75, v229
	v_mov_b32_e32 v76, v230
	v_mov_b32_e32 v77, v231
	v_pk_mul_f32 v[52:53], v[52:53], v[70:71]
	v_mov_b32_e32 v78, v232
	v_mov_b32_e32 v79, v233
	v_mov_b32_e32 v80, v234
	v_mov_b32_e32 v81, v235
	ds_read_b128 v[82:85], v68
	ds_read_b128 v[86:89], v68 offset:1024
	ds_read_b128 v[90:93], v68 offset:2048
	ds_read_b128 v[94:97], v68 offset:3072
	ds_read_b128 v[98:101], v68 offset:7168
	ds_read_b128 v[102:105], v68 offset:6144
	ds_read_b128 v[106:109], v68 offset:5120
	ds_read_b128 v[110:113], v68 offset:4096
	s_waitcnt lgkmcnt(7)
	v_mul_f32_e32 v11, v37, v83
	v_mul_f32_e32 v12, v7, v83
	v_pk_mul_f32 v[54:55], v[114:115], v[62:63] op_sel_hi:[0,1]
	v_fmac_f32_e32 v11, v36, v82
	s_waitcnt lgkmcnt(0)
	v_mul_f32_e32 v33, v37, v111
	v_mul_f32_e32 v62, v7, v111
	v_fmac_f32_e32 v12, v6, v82
	v_fmac_f32_e32 v33, v36, v110
	v_fmac_f32_e32 v62, v6, v110
	v_fmac_f32_e32 v11, v34, v84
	v_fmac_f32_e32 v12, v2, v84
	v_mul_f32_e32 v63, v41, v87
	v_mul_f32_e32 v83, v41, v107
	v_mul_f32_e32 v84, v9, v107
	v_fmac_f32_e32 v33, v34, v112
	v_fmac_f32_e32 v62, v2, v112
	v_fmac_f32_e32 v63, v40, v86
	v_fmac_f32_e32 v83, v40, v106
	v_fmac_f32_e32 v84, v8, v106
	v_fmac_f32_e32 v11, v35, v85
	v_fmac_f32_e32 v33, v35, v113
	v_fmac_f32_e32 v62, v3, v113
	v_mul_f32_e32 v82, v9, v87
	v_fmac_f32_e32 v63, v38, v88
	v_fmac_f32_e32 v83, v38, v108
	v_fmac_f32_e32 v84, v4, v108
	v_add_f32_e32 v11, 0, v11
	v_add_f32_e32 v33, 0, v33
	v_add_f32_e32 v62, 0, v62
	v_fmac_f32_e32 v82, v8, v86
	v_fmac_f32_e32 v63, v39, v89
	v_fmac_f32_e32 v83, v39, v109
	v_fmac_f32_e32 v84, v5, v109
	v_fmac_f32_e32 v12, v3, v85
	v_fmac_f32_e32 v82, v4, v88
	v_add_f32_e32 v11, v11, v63
	v_add_f32_e32 v33, v83, v33
	v_add_f32_e32 v62, v84, v62
	v_mul_f32_e32 v63, v49, v91
	v_mul_f32_e32 v83, v49, v103
	v_mul_f32_e32 v84, v45, v103
	v_add_f32_e32 v12, 0, v12
	v_fmac_f32_e32 v82, v5, v89
	v_fmac_f32_e32 v63, v48, v90
	v_fmac_f32_e32 v83, v48, v102
	v_fmac_f32_e32 v84, v44, v102
	v_add_f32_e32 v12, v12, v82
	v_mul_f32_e32 v82, v45, v91
	v_fmac_f32_e32 v63, v46, v92
	v_fmac_f32_e32 v83, v46, v104
	v_fmac_f32_e32 v84, v42, v104
	v_fmac_f32_e32 v82, v44, v90
	v_fmac_f32_e32 v63, v47, v93
	v_fmac_f32_e32 v83, v47, v105
	v_fmac_f32_e32 v84, v43, v105
	v_fmac_f32_e32 v82, v42, v92
	v_add_f32_e32 v11, v11, v63
	v_add_f32_e32 v33, v83, v33
	v_add_f32_e32 v83, v84, v62
	v_pk_add_f32 v[62:63], v[74:75], 1.0 op_sel_hi:[1,0]
	v_pk_mul_f32 v[70:71], v[54:55], v[70:71]
	v_fmac_f32_e32 v82, v43, v93
	v_pk_mul_f32 v[50:51], v[50:51], v[72:73]
	v_pk_add_f32 v[74:75], v[76:77], 1.0 op_sel_hi:[1,0]
	v_pk_mul_f32 v[72:73], v[56:57], v[72:73]
	v_add_f32_e32 v82, v12, v82
	v_pk_fma_f32 v[56:57], v[52:53], v[62:63], v[78:79]
	v_pk_fma_f32 v[52:53], v[70:71], v[62:63], v[78:79]
	v_pk_fma_f32 v[54:55], v[50:51], v[74:75], v[80:81]
	v_pk_fma_f32 v[50:51], v[72:73], v[74:75], v[80:81]
	v_mul_f32_e32 v12, v57, v95
	v_mul_f32_e32 v72, v53, v95
	v_mul_f32_e32 v73, v57, v99
	v_mul_f32_e32 v74, v53, v99
	v_fmac_f32_e32 v12, v56, v94
	v_fmac_f32_e32 v72, v52, v94
	v_fmac_f32_e32 v73, v56, v98
	v_fmac_f32_e32 v74, v52, v98
	v_fmac_f32_e32 v12, v54, v96
	v_fmac_f32_e32 v72, v50, v96
	v_fmac_f32_e32 v73, v54, v100
	v_fmac_f32_e32 v74, v50, v100
	v_cvt_pk_bf16_f32 v62, v56, v57
	v_cvt_pk_bf16_f32 v63, v54, v55
	v_fmac_f32_e32 v12, v55, v97
	v_fmac_f32_e32 v72, v51, v97
	v_fmac_f32_e32 v73, v55, v101
	v_fmac_f32_e32 v74, v51, v101
	v_cvt_pk_bf16_f32 v70, v52, v53
	v_cvt_pk_bf16_f32 v71, v50, v51
	global_store_dwordx2 v[58:59], v[62:63], off offset:1536
	global_store_dwordx2 v[60:61], v[70:71], off offset:1536
	v_add_f32_e32 v12, v11, v12
	v_add_f32_e32 v58, v82, v72
	v_add_f32_e32 v11, v73, v33
	v_add_f32_e32 v33, v74, v83
	ds_read_b128 v[60:63], v68 offset:8192
	ds_read_b128 v[70:73], v68 offset:9216
	s_waitcnt lgkmcnt(1)
	v_mul_f32_e32 v59, v37, v61
	v_mul_f32_e32 v61, v7, v61
	v_fmac_f32_e32 v59, v36, v60
	v_fmac_f32_e32 v61, v6, v60
	s_waitcnt lgkmcnt(0)
	v_mul_f32_e32 v60, v41, v71
	v_fmac_f32_e32 v59, v34, v62
	v_fmac_f32_e32 v60, v40, v70
	v_fmac_f32_e32 v61, v2, v62
	v_fmac_f32_e32 v59, v35, v63
	v_fmac_f32_e32 v60, v38, v72
	v_add_f32_e32 v59, 0, v59
	v_fmac_f32_e32 v61, v3, v63
	v_fmac_f32_e32 v60, v39, v73
	v_add_f32_e32 v74, 0, v61
	v_add_f32_e32 v59, v59, v60
	v_mul_f32_e32 v71, v9, v71
	ds_read_b128 v[60:63], v68 offset:10240
	v_fmac_f32_e32 v71, v8, v70
	v_fmac_f32_e32 v71, v4, v72
	v_fmac_f32_e32 v71, v5, v73
	v_add_f32_e32 v74, v74, v71
	ds_read_b128 v[70:73], v68 offset:11264
	s_waitcnt lgkmcnt(1)
	v_mul_f32_e32 v75, v49, v61
	v_mul_f32_e32 v61, v45, v61
	v_fmac_f32_e32 v61, v44, v60
	v_fmac_f32_e32 v61, v42, v62
	v_fmac_f32_e32 v61, v43, v63
	v_fmac_f32_e32 v75, v48, v60
	v_add_f32_e32 v60, v74, v61
	s_waitcnt lgkmcnt(0)
	v_mul_f32_e32 v61, v57, v71
	v_fmac_f32_e32 v75, v46, v62
	v_fmac_f32_e32 v61, v56, v70
	v_fmac_f32_e32 v75, v47, v63
	v_fmac_f32_e32 v61, v54, v72
	v_add_f32_e32 v59, v59, v75
	v_fmac_f32_e32 v61, v55, v73
	ds_read_b128 v[74:77], v68 offset:13312
	ds_read_b128 v[78:81], v68 offset:12288
	v_add_f32_e32 v59, v59, v61
	v_mul_f32_e32 v61, v53, v71
	v_fmac_f32_e32 v61, v52, v70
	v_fmac_f32_e32 v61, v50, v72
	v_fmac_f32_e32 v61, v51, v73
	v_add_f32_e32 v60, v60, v61
	s_waitcnt lgkmcnt(0)
	v_mul_f32_e32 v61, v37, v79
	v_fmac_f32_e32 v61, v36, v78
	v_mul_f32_e32 v63, v41, v75
	v_fmac_f32_e32 v61, v34, v80
	v_fmac_f32_e32 v63, v40, v74
	v_fmac_f32_e32 v61, v35, v81
	v_fmac_f32_e32 v63, v38, v76
	ds_read_b128 v[70:73], v68 offset:15360
	ds_read_b128 v[82:85], v68 offset:14336
	v_add_f32_e32 v61, 0, v61
	v_mul_f32_e32 v62, v7, v79
	v_fmac_f32_e32 v63, v39, v77
	v_fmac_f32_e32 v62, v6, v78
	v_add_f32_e32 v61, v63, v61
	v_mul_f32_e32 v63, v9, v75
	v_fmac_f32_e32 v62, v2, v80
	v_fmac_f32_e32 v63, v8, v74
	v_fmac_f32_e32 v62, v3, v81
	v_fmac_f32_e32 v63, v4, v76
	v_add_f32_e32 v62, 0, v62
	v_fmac_f32_e32 v63, v5, v77
	v_add_f32_e32 v62, v63, v62
	s_waitcnt lgkmcnt(0)
	v_mul_f32_e32 v63, v49, v83
	v_fmac_f32_e32 v63, v48, v82
	v_fmac_f32_e32 v63, v46, v84
	v_fmac_f32_e32 v63, v47, v85
	v_add_f32_e32 v61, v63, v61
	v_mul_f32_e32 v63, v45, v83
	v_fmac_f32_e32 v63, v44, v82
	v_fmac_f32_e32 v63, v42, v84
	v_fmac_f32_e32 v63, v43, v85
	v_add_f32_e32 v62, v63, v62
	v_mul_f32_e32 v63, v57, v71
	v_fmac_f32_e32 v63, v56, v70
	v_fmac_f32_e32 v63, v54, v72
	v_fmac_f32_e32 v63, v55, v73
	v_add_f32_e32 v61, v63, v61
	v_mul_f32_e32 v63, v53, v71
	v_fmac_f32_e32 v63, v52, v70
	v_fmac_f32_e32 v63, v50, v72
	v_fmac_f32_e32 v63, v51, v73
	v_add_f32_e32 v62, v63, v62
	ds_read_b128 v[70:73], v68 offset:16384
	ds_read_b128 v[74:77], v68 offset:17408
	s_waitcnt lgkmcnt(1)
	v_mul_f32_e32 v63, v37, v71
	v_mul_f32_e32 v71, v7, v71
	v_fmac_f32_e32 v63, v36, v70
	v_fmac_f32_e32 v71, v6, v70
	s_waitcnt lgkmcnt(0)
	v_mul_f32_e32 v70, v41, v75
	v_fmac_f32_e32 v63, v34, v72
	v_fmac_f32_e32 v70, v40, v74
	v_fmac_f32_e32 v71, v2, v72
	v_fmac_f32_e32 v63, v35, v73
	v_fmac_f32_e32 v70, v38, v76
	v_add_f32_e32 v63, 0, v63
	v_fmac_f32_e32 v71, v3, v73
	v_fmac_f32_e32 v70, v39, v77
	v_add_f32_e32 v78, 0, v71
	v_add_f32_e32 v63, v63, v70
	v_mul_f32_e32 v75, v9, v75
	ds_read_b128 v[70:73], v68 offset:18432
	v_fmac_f32_e32 v75, v8, v74
	v_fmac_f32_e32 v75, v4, v76
	v_fmac_f32_e32 v75, v5, v77
	v_add_f32_e32 v78, v78, v75
	ds_read_b128 v[74:77], v68 offset:19456
	s_waitcnt lgkmcnt(1)
	v_mul_f32_e32 v79, v49, v71
	v_mul_f32_e32 v71, v45, v71
	v_fmac_f32_e32 v71, v44, v70
	v_fmac_f32_e32 v71, v42, v72
	v_fmac_f32_e32 v71, v43, v73
	v_fmac_f32_e32 v79, v48, v70
	v_add_f32_e32 v70, v78, v71
	s_waitcnt lgkmcnt(0)
	v_mul_f32_e32 v71, v57, v75
	v_fmac_f32_e32 v79, v46, v72
	v_fmac_f32_e32 v71, v56, v74
	v_fmac_f32_e32 v79, v47, v73
	v_fmac_f32_e32 v71, v54, v76
	v_add_f32_e32 v63, v63, v79
	v_fmac_f32_e32 v71, v55, v77
	v_add_f32_e32 v63, v63, v71
	v_mul_f32_e32 v71, v53, v75
	v_fmac_f32_e32 v71, v52, v74
	ds_read_b128 v[72:75], v68 offset:21504
	ds_read_b128 v[78:81], v68 offset:20480
	v_fmac_f32_e32 v71, v50, v76
	ds_read_b128 v[82:85], v68 offset:23552
	ds_read_b128 v[86:89], v68 offset:22528
	v_fmac_f32_e32 v71, v51, v77
	s_waitcnt lgkmcnt(3)
	v_mul_f32_e32 v77, v41, v73
	s_waitcnt lgkmcnt(2)
	v_mul_f32_e32 v76, v7, v79
	v_fmac_f32_e32 v76, v6, v78
	v_mul_f32_e32 v73, v9, v73
	v_fmac_f32_e32 v76, v2, v80
	v_fmac_f32_e32 v73, v8, v72
	v_add_f32_e32 v70, v70, v71
	v_mul_f32_e32 v71, v37, v79
	v_fmac_f32_e32 v76, v3, v81
	v_fmac_f32_e32 v73, v4, v74
	v_fmac_f32_e32 v71, v36, v78
	v_add_f32_e32 v76, 0, v76
	v_fmac_f32_e32 v73, v5, v75
	v_fmac_f32_e32 v71, v34, v80
	v_fmac_f32_e32 v77, v40, v72
	v_add_f32_e32 v72, v73, v76
	s_waitcnt lgkmcnt(0)
	v_mul_f32_e32 v73, v49, v87
	v_fmac_f32_e32 v71, v35, v81
	v_fmac_f32_e32 v77, v38, v74
	v_fmac_f32_e32 v73, v48, v86
	v_add_f32_e32 v71, 0, v71
	v_fmac_f32_e32 v77, v39, v75
	v_fmac_f32_e32 v73, v46, v88
	v_add_f32_e32 v71, v77, v71
	v_fmac_f32_e32 v73, v47, v89
	v_add_f32_e32 v71, v73, v71
	v_mul_f32_e32 v73, v45, v87
	v_fmac_f32_e32 v73, v44, v86
	v_fmac_f32_e32 v73, v42, v88
	v_fmac_f32_e32 v73, v43, v89
	v_add_f32_e32 v72, v73, v72
	v_mul_f32_e32 v73, v57, v83
	v_fmac_f32_e32 v73, v56, v82
	v_fmac_f32_e32 v73, v54, v84
	v_fmac_f32_e32 v73, v55, v85
	v_add_f32_e32 v71, v73, v71
	v_mul_f32_e32 v73, v53, v83
	v_fmac_f32_e32 v73, v52, v82
	v_fmac_f32_e32 v73, v50, v84
	v_fmac_f32_e32 v73, v51, v85
	v_add_f32_e32 v72, v73, v72
	ds_read_b128 v[74:77], v68 offset:24576
	ds_read_b128 v[78:81], v68 offset:25600
	s_waitcnt lgkmcnt(1)
	v_mul_f32_e32 v73, v37, v75
	v_mul_f32_e32 v75, v7, v75
	v_fmac_f32_e32 v73, v36, v74
	v_fmac_f32_e32 v75, v6, v74
	s_waitcnt lgkmcnt(0)
	v_mul_f32_e32 v74, v41, v79
	v_fmac_f32_e32 v73, v34, v76
	v_fmac_f32_e32 v74, v40, v78
	v_fmac_f32_e32 v75, v2, v76
	v_fmac_f32_e32 v73, v35, v77
	v_fmac_f32_e32 v74, v38, v80
	v_add_f32_e32 v73, 0, v73
	v_fmac_f32_e32 v75, v3, v77
	v_fmac_f32_e32 v74, v39, v81
	v_add_f32_e32 v82, 0, v75
	v_add_f32_e32 v73, v73, v74
	v_mul_f32_e32 v79, v9, v79
	ds_read_b128 v[74:77], v68 offset:26624
	v_fmac_f32_e32 v79, v8, v78
	v_fmac_f32_e32 v79, v4, v80
	v_fmac_f32_e32 v79, v5, v81
	v_add_f32_e32 v82, v82, v79
	ds_read_b128 v[78:81], v68 offset:27648
	s_waitcnt lgkmcnt(1)
	v_mul_f32_e32 v83, v49, v75
	v_mul_f32_e32 v75, v45, v75
	v_fmac_f32_e32 v75, v44, v74
	v_fmac_f32_e32 v75, v42, v76
	v_fmac_f32_e32 v75, v43, v77
	v_fmac_f32_e32 v83, v48, v74
	v_add_f32_e32 v74, v82, v75
	s_waitcnt lgkmcnt(0)
	v_mul_f32_e32 v75, v57, v79
	v_fmac_f32_e32 v83, v46, v76
	v_fmac_f32_e32 v75, v56, v78
	v_fmac_f32_e32 v83, v47, v77
	v_fmac_f32_e32 v75, v54, v80
	v_add_f32_e32 v73, v73, v83
	v_fmac_f32_e32 v75, v55, v81
	v_add_f32_e32 v73, v73, v75
	v_mul_f32_e32 v75, v53, v79
	v_fmac_f32_e32 v75, v52, v78
	ds_read_b128 v[76:79], v68 offset:29696
	ds_read_b128 v[82:85], v68 offset:28672
	v_fmac_f32_e32 v75, v50, v80
	ds_read_b128 v[86:89], v68 offset:31744
	ds_read_b128 v[90:93], v68 offset:30720
	v_fmac_f32_e32 v75, v51, v81
	s_waitcnt lgkmcnt(3)
	v_mul_f32_e32 v81, v41, v77
	s_waitcnt lgkmcnt(2)
	v_mul_f32_e32 v80, v7, v83
	v_fmac_f32_e32 v80, v6, v82
	v_mul_f32_e32 v77, v9, v77
	v_fmac_f32_e32 v80, v2, v84
	v_fmac_f32_e32 v77, v8, v76
	v_add_f32_e32 v74, v74, v75
	v_mul_f32_e32 v75, v37, v83
	v_fmac_f32_e32 v80, v3, v85
	v_fmac_f32_e32 v77, v4, v78
	v_fmac_f32_e32 v75, v36, v82
	v_add_f32_e32 v80, 0, v80
	v_fmac_f32_e32 v77, v5, v79
	v_fmac_f32_e32 v75, v34, v84
	v_fmac_f32_e32 v81, v40, v76
	v_add_f32_e32 v76, v77, v80
	s_waitcnt lgkmcnt(0)
	v_mul_f32_e32 v77, v49, v91
	v_fmac_f32_e32 v75, v35, v85
	v_fmac_f32_e32 v81, v38, v78
	v_fmac_f32_e32 v77, v48, v90
	v_add_f32_e32 v75, 0, v75
	v_fmac_f32_e32 v81, v39, v79
	v_fmac_f32_e32 v77, v46, v92
	v_add_f32_e32 v75, v81, v75
	v_fmac_f32_e32 v77, v47, v93
	v_add_f32_e32 v75, v77, v75
	v_mul_f32_e32 v77, v45, v91
	v_fmac_f32_e32 v77, v44, v90
	v_fmac_f32_e32 v77, v42, v92
	v_fmac_f32_e32 v77, v43, v93
	v_add_f32_e32 v76, v77, v76
	v_mul_f32_e32 v77, v57, v87
	v_fmac_f32_e32 v77, v56, v86
	v_fmac_f32_e32 v77, v54, v88
	v_fmac_f32_e32 v77, v55, v89
	v_add_f32_e32 v75, v77, v75
	v_mul_f32_e32 v77, v53, v87
	v_fmac_f32_e32 v77, v52, v86
	v_fmac_f32_e32 v77, v50, v88
	v_fmac_f32_e32 v77, v51, v89
	v_add_f32_e32 v76, v77, v76
	ds_read_b128 v[78:81], v68 offset:32768
	ds_read_b128 v[82:85], v68 offset:33792
	s_waitcnt lgkmcnt(1)
	v_mul_f32_e32 v77, v37, v79
	v_mul_f32_e32 v79, v7, v79
	v_fmac_f32_e32 v77, v36, v78
	v_fmac_f32_e32 v79, v6, v78
	s_waitcnt lgkmcnt(0)
	v_mul_f32_e32 v78, v41, v83
	v_fmac_f32_e32 v77, v34, v80
	v_fmac_f32_e32 v78, v40, v82
	v_fmac_f32_e32 v79, v2, v80
	v_fmac_f32_e32 v77, v35, v81
	v_fmac_f32_e32 v78, v38, v84
	v_add_f32_e32 v77, 0, v77
	v_fmac_f32_e32 v79, v3, v81
	v_fmac_f32_e32 v78, v39, v85
	v_add_f32_e32 v86, 0, v79
	v_add_f32_e32 v77, v77, v78
	v_mul_f32_e32 v83, v9, v83
	ds_read_b128 v[78:81], v68 offset:34816
	v_fmac_f32_e32 v83, v8, v82
	v_fmac_f32_e32 v83, v4, v84
	v_fmac_f32_e32 v83, v5, v85
	v_add_f32_e32 v86, v86, v83
	ds_read_b128 v[82:85], v68 offset:35840
	s_waitcnt lgkmcnt(1)
	v_mul_f32_e32 v87, v49, v79
	v_mul_f32_e32 v79, v45, v79
	v_fmac_f32_e32 v79, v44, v78
	v_fmac_f32_e32 v79, v42, v80
	v_fmac_f32_e32 v79, v43, v81
	v_fmac_f32_e32 v87, v48, v78
	v_add_f32_e32 v78, v86, v79
	s_waitcnt lgkmcnt(0)
	v_mul_f32_e32 v79, v57, v83
	v_fmac_f32_e32 v87, v46, v80
	v_fmac_f32_e32 v79, v56, v82
	v_fmac_f32_e32 v87, v47, v81
	v_fmac_f32_e32 v79, v54, v84
	v_add_f32_e32 v77, v77, v87
	v_fmac_f32_e32 v79, v55, v85
	v_add_f32_e32 v77, v77, v79
	v_mul_f32_e32 v79, v53, v83
	v_fmac_f32_e32 v79, v52, v82
	ds_read_b128 v[80:83], v68 offset:37888
	ds_read_b128 v[86:89], v68 offset:36864
	v_fmac_f32_e32 v79, v50, v84
	ds_read_b128 v[90:93], v68 offset:39936
	ds_read_b128 v[94:97], v68 offset:38912
	v_fmac_f32_e32 v79, v51, v85
	s_waitcnt lgkmcnt(3)
	v_mul_f32_e32 v85, v41, v81
	s_waitcnt lgkmcnt(2)
	v_mul_f32_e32 v84, v7, v87
	v_fmac_f32_e32 v84, v6, v86
	v_mul_f32_e32 v81, v9, v81
	v_fmac_f32_e32 v84, v2, v88
	v_fmac_f32_e32 v81, v8, v80
	v_add_f32_e32 v78, v78, v79
	v_mul_f32_e32 v79, v37, v87
	v_fmac_f32_e32 v84, v3, v89
	v_fmac_f32_e32 v81, v4, v82
	v_fmac_f32_e32 v79, v36, v86
	v_add_f32_e32 v84, 0, v84
	v_fmac_f32_e32 v81, v5, v83
	v_fmac_f32_e32 v79, v34, v88
	v_fmac_f32_e32 v85, v40, v80
	v_add_f32_e32 v80, v81, v84
	s_waitcnt lgkmcnt(0)
	v_mul_f32_e32 v81, v49, v95
	v_fmac_f32_e32 v79, v35, v89
	v_fmac_f32_e32 v85, v38, v82
	v_fmac_f32_e32 v81, v48, v94
	v_add_f32_e32 v79, 0, v79
	v_fmac_f32_e32 v85, v39, v83
	v_fmac_f32_e32 v81, v46, v96
	v_add_f32_e32 v79, v85, v79
	v_fmac_f32_e32 v81, v47, v97
	v_add_f32_e32 v79, v81, v79
	v_mul_f32_e32 v81, v45, v95
	v_fmac_f32_e32 v81, v44, v94
	v_fmac_f32_e32 v81, v42, v96
	v_fmac_f32_e32 v81, v43, v97
	v_add_f32_e32 v80, v81, v80
	v_mul_f32_e32 v81, v57, v91
	v_fmac_f32_e32 v81, v56, v90
	v_fmac_f32_e32 v81, v54, v92
	v_fmac_f32_e32 v81, v55, v93
	v_add_f32_e32 v79, v81, v79
	v_mul_f32_e32 v81, v53, v91
	v_fmac_f32_e32 v81, v52, v90
	v_fmac_f32_e32 v81, v50, v92
	v_fmac_f32_e32 v81, v51, v93
	v_add_f32_e32 v80, v81, v80
	ds_read_b128 v[82:85], v68 offset:40960
	ds_read_b128 v[86:89], v68 offset:41984
	s_waitcnt lgkmcnt(1)
	v_mul_f32_e32 v81, v37, v83
	v_mul_f32_e32 v83, v7, v83
	v_fmac_f32_e32 v81, v36, v82
	v_fmac_f32_e32 v83, v6, v82
	s_waitcnt lgkmcnt(0)
	v_mul_f32_e32 v82, v41, v87
	v_fmac_f32_e32 v81, v34, v84
	v_fmac_f32_e32 v82, v40, v86
	v_mul_f32_e32 v87, v9, v87
	v_fmac_f32_e32 v83, v2, v84
	v_fmac_f32_e32 v81, v35, v85
	v_fmac_f32_e32 v82, v38, v88
	v_fmac_f32_e32 v87, v8, v86
	v_add_f32_e32 v81, 0, v81
	v_fmac_f32_e32 v83, v3, v85
	v_fmac_f32_e32 v82, v39, v89
	v_fmac_f32_e32 v87, v4, v88
	v_add_f32_e32 v90, 0, v83
	v_add_f32_e32 v81, v81, v82
	ds_read_b128 v[82:85], v68 offset:43008
	v_fmac_f32_e32 v87, v5, v89
	v_add_f32_e32 v90, v90, v87
	ds_read_b128 v[86:89], v68 offset:44032
	s_waitcnt lgkmcnt(1)
	v_mul_f32_e32 v91, v49, v83
	v_mul_f32_e32 v83, v45, v83
	v_fmac_f32_e32 v91, v48, v82
	v_fmac_f32_e32 v83, v44, v82
	s_waitcnt lgkmcnt(0)
	v_mul_f32_e32 v82, v57, v87
	v_fmac_f32_e32 v91, v46, v84
	v_fmac_f32_e32 v82, v56, v86
	v_fmac_f32_e32 v91, v47, v85
	v_fmac_f32_e32 v83, v42, v84
	v_fmac_f32_e32 v82, v54, v88
	v_add_f32_e32 v81, v81, v91
	v_fmac_f32_e32 v83, v43, v85
	v_fmac_f32_e32 v82, v55, v89
	v_add_f32_e32 v94, v90, v83
	v_add_f32_e32 v81, v81, v82
	ds_read_b128 v[82:85], v68 offset:46080
	ds_read_b128 v[90:93], v68 offset:45056
	v_mul_f32_e32 v87, v53, v87
	v_fmac_f32_e32 v87, v52, v86
	v_fmac_f32_e32 v87, v50, v88
	v_fmac_f32_e32 v87, v51, v89
	s_waitcnt lgkmcnt(0)
	v_mul_f32_e32 v99, v37, v91
	v_mul_f32_e32 v91, v7, v91
	v_add_f32_e32 v98, v94, v87
	ds_read_b128 v[86:89], v68 offset:48128
	ds_read_b128 v[94:97], v68 offset:47104
	v_fmac_f32_e32 v91, v6, v90
	v_fmac_f32_e32 v91, v2, v92
	v_fmac_f32_e32 v91, v3, v93
	v_fmac_f32_e32 v99, v36, v90
	v_add_f32_e32 v90, 0, v91
	v_mul_f32_e32 v91, v41, v83
	v_mul_f32_e32 v83, v9, v83
	v_fmac_f32_e32 v91, v40, v82
	v_fmac_f32_e32 v83, v8, v82
	v_fmac_f32_e32 v91, v38, v84
	v_fmac_f32_e32 v83, v4, v84
	s_waitcnt lgkmcnt(0)
	v_mul_f32_e32 v84, v45, v95
	v_fmac_f32_e32 v84, v44, v94
	v_fmac_f32_e32 v83, v5, v85
	v_fmac_f32_e32 v84, v42, v96
	v_fmac_f32_e32 v99, v34, v92
	v_add_f32_e32 v82, v83, v90
	v_mul_f32_e32 v83, v49, v95
	v_fmac_f32_e32 v84, v43, v97
	v_fmac_f32_e32 v99, v35, v93
	v_fmac_f32_e32 v83, v48, v94
	v_add_f32_e32 v82, v84, v82
	v_mul_f32_e32 v84, v57, v87
	v_add_f32_e32 v99, 0, v99
	v_fmac_f32_e32 v91, v39, v85
	v_fmac_f32_e32 v83, v46, v96
	v_fmac_f32_e32 v84, v56, v86
	v_add_f32_e32 v91, v91, v99
	v_fmac_f32_e32 v83, v47, v97
	v_fmac_f32_e32 v84, v54, v88
	v_add_f32_e32 v83, v83, v91
	v_fmac_f32_e32 v84, v55, v89
	v_add_f32_e32 v99, v84, v83
	v_mul_f32_e32 v83, v53, v87
	v_fmac_f32_e32 v83, v52, v86
	v_fmac_f32_e32 v83, v50, v88
	v_fmac_f32_e32 v83, v51, v89
	v_add_f32_e32 v100, v83, v82
	ds_read_b128 v[82:85], v68 offset:49152
	ds_read_b128 v[86:89], v68 offset:50176
	s_waitcnt lgkmcnt(1)
	v_mul_f32_e32 v90, v37, v83
	v_mul_f32_e32 v83, v7, v83
	v_fmac_f32_e32 v90, v36, v82
	v_fmac_f32_e32 v83, v6, v82
	v_fmac_f32_e32 v90, v34, v84
	v_fmac_f32_e32 v83, v2, v84
	v_fmac_f32_e32 v90, v35, v85
	v_fmac_f32_e32 v83, v3, v85
	v_add_f32_e32 v82, 0, v90
	v_add_f32_e32 v90, 0, v83
	s_waitcnt lgkmcnt(0)
	v_mul_f32_e32 v83, v41, v87
	v_fmac_f32_e32 v83, v40, v86
	v_mul_f32_e32 v87, v9, v87
	v_fmac_f32_e32 v83, v38, v88
	v_fmac_f32_e32 v87, v8, v86
	v_fmac_f32_e32 v83, v39, v89
	v_fmac_f32_e32 v87, v4, v88
	v_add_f32_e32 v91, v82, v83
	ds_read_b128 v[82:85], v68 offset:51200
	v_fmac_f32_e32 v87, v5, v89
	v_add_f32_e32 v90, v90, v87
	ds_read_b128 v[86:89], v68 offset:52224
	s_waitcnt lgkmcnt(1)
	v_mul_f32_e32 v92, v49, v83
	v_mul_f32_e32 v83, v45, v83
	v_fmac_f32_e32 v92, v48, v82
	v_fmac_f32_e32 v83, v44, v82
	s_waitcnt lgkmcnt(0)
	v_mul_f32_e32 v82, v57, v87
	v_fmac_f32_e32 v92, v46, v84
	v_fmac_f32_e32 v82, v56, v86
	v_fmac_f32_e32 v92, v47, v85
	v_fmac_f32_e32 v83, v42, v84
	v_fmac_f32_e32 v82, v54, v88
	v_add_f32_e32 v91, v91, v92
	v_fmac_f32_e32 v83, v43, v85
	v_fmac_f32_e32 v82, v55, v89
	v_add_f32_e32 v94, v90, v83
	v_add_f32_e32 v101, v91, v82
	ds_read_b128 v[82:85], v68 offset:54272
	ds_read_b128 v[90:93], v68 offset:53248
	v_mul_f32_e32 v87, v53, v87
	v_fmac_f32_e32 v87, v52, v86
	v_fmac_f32_e32 v87, v50, v88
	v_fmac_f32_e32 v87, v51, v89
	s_waitcnt lgkmcnt(0)
	v_mul_f32_e32 v103, v37, v91
	v_mul_f32_e32 v91, v7, v91
	v_add_f32_e32 v102, v94, v87
	ds_read_b128 v[86:89], v68 offset:56320
	ds_read_b128 v[94:97], v68 offset:55296
	v_fmac_f32_e32 v91, v6, v90
	v_fmac_f32_e32 v91, v2, v92
	v_fmac_f32_e32 v91, v3, v93
	v_fmac_f32_e32 v103, v36, v90
	v_add_f32_e32 v90, 0, v91
	v_mul_f32_e32 v91, v41, v83
	v_mul_f32_e32 v83, v9, v83
	v_fmac_f32_e32 v91, v40, v82
	v_fmac_f32_e32 v83, v8, v82
	v_fmac_f32_e32 v91, v38, v84
	v_fmac_f32_e32 v83, v4, v84
	s_waitcnt lgkmcnt(0)
	v_mul_f32_e32 v84, v45, v95
	v_fmac_f32_e32 v84, v44, v94
	v_fmac_f32_e32 v83, v5, v85
	v_fmac_f32_e32 v84, v42, v96
	v_fmac_f32_e32 v103, v34, v92
	v_add_f32_e32 v82, v83, v90
	v_mul_f32_e32 v83, v49, v95
	v_fmac_f32_e32 v84, v43, v97
	v_fmac_f32_e32 v103, v35, v93
	v_fmac_f32_e32 v83, v48, v94
	v_add_f32_e32 v82, v84, v82
	v_mul_f32_e32 v84, v57, v87
	v_add_f32_e32 v103, 0, v103
	v_fmac_f32_e32 v91, v39, v85
	v_fmac_f32_e32 v83, v46, v96
	v_fmac_f32_e32 v84, v56, v86
	v_add_f32_e32 v91, v91, v103
	v_fmac_f32_e32 v83, v47, v97
	v_fmac_f32_e32 v84, v54, v88
	v_add_f32_e32 v83, v83, v91
	v_fmac_f32_e32 v84, v55, v89
	v_add_f32_e32 v103, v84, v83
	v_mul_f32_e32 v83, v53, v87
	v_fmac_f32_e32 v83, v52, v86
	v_fmac_f32_e32 v83, v50, v88
	v_fmac_f32_e32 v83, v51, v89
	v_add_f32_e32 v104, v83, v82
	ds_read_b128 v[82:85], v68 offset:57344
	ds_read_b128 v[86:89], v68 offset:58368
	s_waitcnt lgkmcnt(1)
	v_mul_f32_e32 v90, v37, v83
	v_mul_f32_e32 v83, v7, v83
	v_fmac_f32_e32 v90, v36, v82
	v_fmac_f32_e32 v83, v6, v82
	v_fmac_f32_e32 v90, v34, v84
	v_fmac_f32_e32 v83, v2, v84
	v_fmac_f32_e32 v90, v35, v85
	v_fmac_f32_e32 v83, v3, v85
	v_add_f32_e32 v82, 0, v90
	v_add_f32_e32 v90, 0, v83
	s_waitcnt lgkmcnt(0)
	v_mul_f32_e32 v83, v41, v87
	v_fmac_f32_e32 v83, v40, v86
	v_mul_f32_e32 v87, v9, v87
	v_fmac_f32_e32 v83, v38, v88
	v_fmac_f32_e32 v87, v8, v86
	v_fmac_f32_e32 v83, v39, v89
	v_fmac_f32_e32 v87, v4, v88
	v_add_f32_e32 v91, v82, v83
	ds_read_b128 v[82:85], v68 offset:59392
	v_fmac_f32_e32 v87, v5, v89
	v_add_f32_e32 v90, v90, v87
	ds_read_b128 v[86:89], v68 offset:60416
	s_waitcnt lgkmcnt(1)
	v_mul_f32_e32 v92, v49, v83
	v_mul_f32_e32 v83, v45, v83
	v_fmac_f32_e32 v92, v48, v82
	v_fmac_f32_e32 v83, v44, v82
	s_waitcnt lgkmcnt(0)
	v_mul_f32_e32 v82, v57, v87
	v_fmac_f32_e32 v92, v46, v84
	v_fmac_f32_e32 v82, v56, v86
	v_fmac_f32_e32 v92, v47, v85
	v_fmac_f32_e32 v83, v42, v84
	v_fmac_f32_e32 v82, v54, v88
	v_add_f32_e32 v91, v91, v92
	v_fmac_f32_e32 v83, v43, v85
	v_fmac_f32_e32 v82, v55, v89
	v_add_f32_e32 v94, v90, v83
	v_add_f32_e32 v105, v91, v82
	v_mul_f32_e32 v87, v53, v87
	ds_read_b128 v[82:85], v68 offset:62464
	ds_read_b128 v[90:93], v68 offset:61440
	v_fmac_f32_e32 v87, v52, v86
	v_fmac_f32_e32 v87, v50, v88
	v_fmac_f32_e32 v87, v51, v89
	v_add_f32_e32 v106, v94, v87
	ds_read_b128 v[86:89], v68 offset:64512
	ds_read_b128 v[94:97], v68 offset:63488
	s_waitcnt lgkmcnt(2)
	v_mul_f32_e32 v7, v7, v91
	v_fmac_f32_e32 v7, v6, v90
	v_mul_f32_e32 v37, v37, v91
	v_fmac_f32_e32 v7, v2, v92
	v_mul_f32_e32 v6, v9, v83
	v_fmac_f32_e32 v37, v36, v90
	v_fmac_f32_e32 v7, v3, v93
	v_mul_f32_e32 v3, v41, v83
	v_fmac_f32_e32 v6, v8, v82
	v_fmac_f32_e32 v37, v34, v92
	v_fmac_f32_e32 v3, v40, v82
	v_fmac_f32_e32 v6, v4, v84
	s_waitcnt lgkmcnt(0)
	v_mul_f32_e32 v4, v49, v95
	v_fmac_f32_e32 v37, v35, v93
	v_fmac_f32_e32 v3, v38, v84
	v_fmac_f32_e32 v4, v48, v94
	v_add_f32_e32 v34, 0, v37
	v_fmac_f32_e32 v3, v39, v85
	v_fmac_f32_e32 v4, v46, v96
	v_add_f32_e32 v3, v3, v34
	v_fmac_f32_e32 v4, v47, v97
	v_add_f32_e32 v3, v4, v3
	v_mul_f32_e32 v4, v45, v95
	v_fmac_f32_e32 v4, v44, v94
	v_add_f32_e32 v2, 0, v7
	v_fmac_f32_e32 v6, v5, v85
	v_fmac_f32_e32 v4, v42, v96
	v_add_f32_e32 v2, v6, v2
	v_fmac_f32_e32 v4, v43, v97
	v_add_f32_e32 v2, v4, v2
	v_mul_f32_e32 v4, v57, v87
	v_fmac_f32_e32 v4, v56, v86
	v_fmac_f32_e32 v4, v54, v88
	v_fmac_f32_e32 v4, v55, v89
	v_add_f32_e32 v3, v4, v3
	v_mul_f32_e32 v4, v53, v87
	v_fmac_f32_e32 v4, v52, v86
	v_fmac_f32_e32 v4, v50, v88
	v_fmac_f32_e32 v4, v51, v89
	v_add_f32_e32 v2, v4, v2
	v_cndmask_b32_e64 v4, v12, v58, s[0:1]
	ds_bpermute_b32 v4, v1, v4
	v_cndmask_b32_e64 v5, v58, v12, s[0:1]
	v_cndmask_b32_e64 v7, v11, v33, s[0:1]
	ds_bpermute_b32 v7, v1, v7
	v_cndmask_b32_e64 v8, v61, v62, s[0:1]
	s_waitcnt lgkmcnt(1)
	v_add_f32_e32 v4, v5, v4
	v_cndmask_b32_e64 v5, v59, v60, s[0:1]
	ds_bpermute_b32 v5, v1, v5
	ds_bpermute_b32 v8, v1, v8
	v_cndmask_b32_e64 v9, v63, v70, s[0:1]
	v_cndmask_b32_e64 v6, v33, v11, s[0:1]
	ds_bpermute_b32 v9, v1, v9
	v_cndmask_b32_e64 v11, v71, v72, s[0:1]
	ds_bpermute_b32 v11, v1, v11
	v_cndmask_b32_e64 v12, v73, v74, s[0:1]
	s_waitcnt lgkmcnt(4)
	v_add_f32_e32 v6, v6, v7
	v_cndmask_b32_e64 v7, v60, v59, s[0:1]
	ds_bpermute_b32 v12, v1, v12
	v_cndmask_b32_e64 v33, v75, v76, s[0:1]
	s_waitcnt lgkmcnt(4)
	v_add_f32_e32 v5, v7, v5
	v_cndmask_b32_e64 v7, v62, v61, s[0:1]
	ds_bpermute_b32 v33, v1, v33
	v_cndmask_b32_e64 v34, v77, v78, s[0:1]
	s_waitcnt lgkmcnt(4)
	v_add_f32_e32 v7, v7, v8
	v_cndmask_b32_e64 v8, v70, v63, s[0:1]
	ds_bpermute_b32 v34, v1, v34
	v_cndmask_b32_e64 v35, v79, v80, s[0:1]
	s_waitcnt lgkmcnt(4)
	v_add_f32_e32 v8, v8, v9
	v_cndmask_b32_e64 v9, v72, v71, s[0:1]
	ds_bpermute_b32 v35, v1, v35
	s_waitcnt lgkmcnt(4)
	v_add_f32_e32 v9, v9, v11
	v_cndmask_b32_e64 v11, v74, v73, s[0:1]
	s_waitcnt lgkmcnt(3)
	v_add_f32_e32 v11, v11, v12
	v_cndmask_b32_e64 v12, v76, v75, s[0:1]
	s_waitcnt lgkmcnt(2)
	v_add_f32_e32 v12, v12, v33
	v_cndmask_b32_e64 v33, v78, v77, s[0:1]
	v_cndmask_b32_e64 v36, v81, v98, s[0:1]
	s_waitcnt lgkmcnt(1)
	v_add_f32_e32 v33, v33, v34
	v_cndmask_b32_e64 v34, v80, v79, s[0:1]
	ds_bpermute_b32 v36, v1, v36
	v_cndmask_b32_e64 v37, v99, v100, s[0:1]
	s_waitcnt lgkmcnt(1)
	v_add_f32_e32 v34, v34, v35
	ds_bpermute_b32 v37, v1, v37
	v_cndmask_b32_e64 v38, v101, v102, s[0:1]
	v_cndmask_b32_e64 v41, v3, v2, s[0:1]
	v_cndmask_b32_e64 v2, v2, v3, s[0:1]
	v_cndmask_b32_e64 v3, v33, v4, s[6:7]
	v_cndmask_b32_e64 v4, v4, v33, s[6:7]
	ds_bpermute_b32 v38, v1, v38
	ds_bpermute_b32 v4, v31, v4
	v_cndmask_b32_e64 v33, v6, v34, s[6:7]
	ds_bpermute_b32 v33, v31, v33
	v_cndmask_b32_e64 v35, v98, v81, s[0:1]
	s_waitcnt lgkmcnt(4)
	v_add_f32_e32 v35, v35, v36
	v_cndmask_b32_e64 v36, v100, v99, s[0:1]
	s_waitcnt lgkmcnt(3)
	v_add_f32_e32 v36, v36, v37
	v_cndmask_b32_e64 v37, v102, v101, s[0:1]
	v_cndmask_b32_e64 v39, v103, v104, s[0:1]
	s_waitcnt lgkmcnt(2)
	v_add_f32_e32 v37, v37, v38
	ds_bpermute_b32 v39, v1, v39
	v_cndmask_b32_e64 v40, v105, v106, s[0:1]
	s_waitcnt lgkmcnt(2)
	v_add_f32_e32 v3, v3, v4
	v_cndmask_b32_e64 v4, v34, v6, s[6:7]
	v_cndmask_b32_e64 v6, v36, v7, s[6:7]
	v_cndmask_b32_e64 v7, v7, v36, s[6:7]
	ds_bpermute_b32 v40, v1, v40
	ds_bpermute_b32 v41, v1, v41
	s_waitcnt lgkmcnt(3)
	v_add_f32_e32 v4, v4, v33
	ds_bpermute_b32 v7, v31, v7
	v_cndmask_b32_e64 v33, v8, v37, s[6:7]
	ds_bpermute_b32 v33, v31, v33
	v_cndmask_b32_e64 v38, v104, v103, s[0:1]
	s_waitcnt lgkmcnt(4)
	v_add_f32_e32 v38, v38, v39
	v_cndmask_b32_e64 v39, v106, v105, s[0:1]
	s_waitcnt lgkmcnt(3)
	v_add_f32_e32 v39, v39, v40
	s_waitcnt lgkmcnt(2)
	v_add_f32_e32 v2, v2, v41
	s_waitcnt lgkmcnt(1)
	v_add_f32_e32 v6, v6, v7
	v_cndmask_b32_e64 v7, v37, v8, s[6:7]
	v_cndmask_b32_e64 v40, v5, v35, s[6:7]
	v_cndmask_b32_e64 v34, v9, v38, s[6:7]
	s_waitcnt lgkmcnt(0)
	v_add_f32_e32 v7, v7, v33
	v_cndmask_b32_e64 v8, v38, v9, s[6:7]
	v_cndmask_b32_e64 v9, v39, v11, s[6:7]
	v_cndmask_b32_e64 v11, v11, v39, s[6:7]
	v_cndmask_b32_e64 v33, v12, v2, s[6:7]
	ds_bpermute_b32 v40, v31, v40
	ds_bpermute_b32 v34, v31, v34
	ds_bpermute_b32 v11, v31, v11
	ds_bpermute_b32 v33, v31, v33
	v_cndmask_b32_e64 v5, v35, v5, s[6:7]
	v_cndmask_b32_e64 v2, v2, v12, s[6:7]
	s_waitcnt lgkmcnt(3)
	v_add_f32_e32 v5, v5, v40
	s_waitcnt lgkmcnt(2)
	v_add_f32_e32 v8, v8, v34
	s_waitcnt lgkmcnt(1)
	v_add_f32_e32 v9, v9, v11
	s_waitcnt lgkmcnt(0)
	v_add_f32_e32 v2, v2, v33
	v_cndmask_b32_e64 v34, v3, v7, s[8:9]
	v_cndmask_b32_e64 v3, v7, v3, s[8:9]
	v_cndmask_b32_e64 v7, v8, v4, s[8:9]
	v_cndmask_b32_e64 v4, v4, v8, s[8:9]
	v_cndmask_b32_e64 v8, v5, v9, s[8:9]
	v_cndmask_b32_e64 v11, v6, v2, s[8:9]
	ds_bpermute_b32 v34, v64, v34
	ds_bpermute_b32 v4, v64, v4
	ds_bpermute_b32 v8, v64, v8
	ds_bpermute_b32 v11, v64, v11
	v_cndmask_b32_e64 v5, v9, v5, s[8:9]
	v_cndmask_b32_e64 v2, v2, v6, s[8:9]
	s_waitcnt lgkmcnt(3)
	v_add_f32_e32 v3, v3, v34
	s_waitcnt lgkmcnt(2)
	v_add_f32_e32 v4, v7, v4
	s_waitcnt lgkmcnt(1)
	v_add_f32_e32 v5, v5, v8
	s_waitcnt lgkmcnt(0)
	v_add_f32_e32 v2, v2, v11
	v_cndmask_b32_e64 v6, v3, v5, s[10:11]
	v_cndmask_b32_e64 v7, v4, v2, s[10:11]
	ds_bpermute_b32 v6, v65, v6
	ds_bpermute_b32 v7, v65, v7
	v_cndmask_b32_e64 v3, v5, v3, s[10:11]
	v_cndmask_b32_e64 v2, v2, v4, s[10:11]
	s_waitcnt lgkmcnt(1)
	v_add_f32_e32 v3, v3, v6
	s_waitcnt lgkmcnt(0)
	v_add_f32_e32 v2, v2, v7
	v_cndmask_b32_e64 v4, v3, v2, s[12:13]
	ds_bpermute_b32 v4, v66, v4
	v_cndmask_b32_e64 v2, v2, v3, s[12:13]
	s_waitcnt lgkmcnt(0)
	v_add_f32_e32 v2, v2, v4
	ds_bpermute_b32 v3, v67, v2
	s_waitcnt lgkmcnt(0)
	v_add_f32_e32 v2, v2, v3
	ds_bpermute_b32 v3, v66, v2
	s_waitcnt lgkmcnt(0)
	v_max_f32_e32 v3, v3, v3
	v_max_f32_e32 v3, v2, v3
	ds_bpermute_b32 v4, v65, v3
	s_waitcnt lgkmcnt(0)
	v_max_f32_e32 v4, v4, v4
	v_max_f32_e32 v3, v3, v4
	ds_bpermute_b32 v4, v64, v3
	s_waitcnt lgkmcnt(0)
	v_max_f32_e32 v4, v4, v4
	v_max_f32_e32 v3, v3, v4
	ds_bpermute_b32 v4, v31, v3
	s_waitcnt lgkmcnt(0)
	v_max_f32_e32 v4, v4, v4
	v_max_f32_e32 v3, v3, v4
	v_sub_f32_e32 v2, v2, v3
	v_mul_f32_e32 v2, 0x3fb8aa3b, v2
	v_exp_f32_e32 v2, v2
	ds_bpermute_b32 v3, v66, v2
	s_waitcnt lgkmcnt(0)
	v_add_f32_e32 v3, v2, v3
	ds_bpermute_b32 v4, v65, v3
	s_waitcnt lgkmcnt(0)
	v_add_f32_e32 v3, v3, v4
	ds_bpermute_b32 v4, v64, v3
	s_waitcnt lgkmcnt(0)
	v_add_f32_e32 v3, v3, v4
	ds_bpermute_b32 v4, v31, v3
	s_and_saveexec_b64 s[4:5], s[14:15]
	s_cbranch_execz .LBB0_640
	s_waitcnt lgkmcnt(0)
	v_add_f32_e32 v3, v3, v4
	v_div_scale_f32 v4, s[28:29], v3, v3, v2
	v_rcp_f32_e32 v5, v4
	v_ashrrev_i32_e32 v33, 31, v32
	v_and_or_b32 v6, v10, s25, v69
	v_lshlrev_b32_e32 v12, 2, v6
	v_fma_f32 v7, -v4, v5, 1.0
	v_fmac_f32_e32 v5, v7, v5
	v_div_scale_f32 v7, vcc, v2, v3, v2
	v_mul_f32_e32 v8, v7, v5
	v_fma_f32 v9, -v4, v8, v7
	v_fmac_f32_e32 v8, v9, v5
	v_fma_f32 v4, -v4, v8, v7
	v_div_fmas_f32 v4, v4, v5, v8
	v_div_fixup_f32 v4, v4, v3, v2
	v_lshlrev_b64 v[2:3], 18, v[32:33]
	v_lshl_add_u64 v[2:3], v[18:19], 0, v[2:3]
	v_lshl_add_u64 v[2:3], v[2:3], 0, v[12:13]
	global_store_dword v[2:3], v4, off sc1
	s_branch .LBB0_640

.LBB0_680:
	s_andn2_saveexec_b64 s[6:7], s[6:7]
	s_cbranch_execz .LBB0_700
	s_mov_b64 s[6:7], exec
	s_nop 0
	s_waitcnt lgkmcnt(0)
	s_waitcnt vmcnt(0)
	v_mbcnt_lo_u32_b32 v2, s6, 0
	v_mbcnt_hi_u32_b32 v2, s7, v2
	v_cmp_eq_u32_e32 vcc, 0, v2
	s_and_saveexec_b64 s[8:9], vcc
	s_cbranch_execz .LBB0_683
	s_bcnt1_i32_b64 s6, s[6:7]
	v_mov_b32_e32 v3, 0x3000
	v_mov_b32_e32 v4, s6
	global_atomic_add v3, v3, v4, s[92:93] offset:1024 sc0

.LBB0_1230:
	v_ashrrev_i32_e32 v11, 31, v10
	v_lshlrev_b64 v[44:45], 11, v[10:11]
	v_lshl_add_u64 v[2:3], v[14:15], 0, v[44:45]
	global_load_dwordx2 v[46:47], v[2:3], off
	global_load_dwordx2 v[50:51], v[2:3], off offset:512
	global_load_dwordx2 v[52:53], v[2:3], off offset:1024
	global_load_dwordx2 v[54:55], v[2:3], off offset:1536
	s_waitcnt lgkmcnt(0)
	v_add_u32_e32 v4, 1, v10
	v_ashrrev_i32_e32 v5, 31, v4
	v_lshlrev_b64 v[66:67], 11, v[4:5]
	v_lshl_add_u64 v[2:3], v[14:15], 0, v[66:67]
	global_load_dwordx2 v[62:63], v[2:3], off
	global_load_dwordx2 v[64:65], v[2:3], off offset:512
	global_load_dwordx2 v[68:69], v[2:3], off offset:1024
	global_load_dwordx2 v[76:77], v[2:3], off offset:1536
	v_ashrrev_i32_e32 v38, 12, v10
	v_mul_hi_i32_i24_e32 v7, 0x6000, v38
	v_mul_i32_i24_e32 v6, 0x6000, v38
	v_lshl_add_u64 v[6:7], s[44:45], 0, v[6:7]
	v_lshl_add_u64 v[60:61], v[6:7], 0, s[20:21]
	v_lshl_add_u64 v[48:49], v[6:7], 0, s[22:23]
	v_lshl_add_u64 v[6:7], v[60:61], 0, v[28:29]
	v_lshl_add_u64 v[40:41], v[48:49], 0, v[28:29]
	global_load_dwordx4 v[200:203], v[18:19], off
	v_lshl_add_u64 v[236:237], v[48:49], 0, v[30:31]
	global_load_dwordx4 v[204:207], v[236:237], off
	v_lshl_add_u64 v[236:237], v[60:61], 0, v[30:31]
	global_load_dwordx4 v[208:211], v[236:237], off
	global_load_dwordx4 v[212:215], v[20:21], off
	v_lshl_add_u64 v[236:237], v[48:49], 0, v[32:33]
	global_load_dwordx4 v[216:219], v[236:237], off
	v_lshl_add_u64 v[236:237], v[60:61], 0, v[32:33]
	global_load_dwordx4 v[220:223], v[236:237], off
	global_load_dwordx4 v[224:227], v[22:23], off
	v_lshl_add_u64 v[236:237], v[48:49], 0, v[34:35]
	global_load_dwordx4 v[228:231], v[236:237], off
	v_lshl_add_u64 v[236:237], v[60:61], 0, v[34:35]
	global_load_dwordx4 v[232:235], v[236:237], off
	global_load_dwordx4 v[2:5], v[16:17], off
	s_nop 0
	global_load_dwordx4 v[6:9], v[6:7], off
	s_nop 0
	global_load_dwordx4 v[40:43], v[40:41], off
	v_lshl_add_u64 v[66:67], v[26:27], 0, v[66:67]
	s_waitcnt vmcnt(19)
	v_and_b32_e32 v81, 0xffff0000, v46
	s_waitcnt vmcnt(18)
	v_and_b32_e32 v85, 0xffff0000, v50
	s_waitcnt vmcnt(17)
	v_and_b32_e32 v89, 0xffff0000, v52
	s_waitcnt vmcnt(16)
	v_and_b32_e32 v59, 0xffff0000, v54
	v_lshlrev_b32_e32 v88, 16, v52
	v_lshlrev_b32_e32 v58, 16, v54
	v_mov_b32_e32 v102, v89
	v_mov_b32_e32 v103, v59
	v_lshlrev_b32_e32 v86, 16, v53
	v_lshlrev_b32_e32 v56, 16, v55
	v_mov_b32_e32 v100, v88
	v_mov_b32_e32 v101, v58
	v_pk_mul_f32 v[102:103], v[102:103], v[102:103]
	v_lshlrev_b32_e32 v80, 16, v46
	v_lshlrev_b32_e32 v82, 16, v51
	v_and_b32_e32 v83, 0xffff0000, v51
	v_lshlrev_b32_e32 v84, 16, v50
	v_and_b32_e32 v87, 0xffff0000, v53
	v_and_b32_e32 v57, 0xffff0000, v55
	s_waitcnt vmcnt(15)
	v_and_b32_e32 v51, 0xffff0000, v62
	v_mov_b32_e32 v90, v81
	v_mov_b32_e32 v91, v85
	s_waitcnt vmcnt(14)
	v_lshlrev_b32_e32 v92, 16, v65
	v_and_b32_e32 v93, 0xffff0000, v65
	v_lshlrev_b32_e32 v94, 16, v64
	v_and_b32_e32 v95, 0xffff0000, v64
	v_mov_b32_e32 v64, v86
	v_mov_b32_e32 v65, v56
	v_pk_fma_f32 v[100:101], v[100:101], v[100:101], v[102:103]
	v_lshlrev_b32_e32 v78, 16, v47
	v_and_b32_e32 v79, 0xffff0000, v47
	v_lshlrev_b32_e32 v46, 16, v63
	v_and_b32_e32 v47, 0xffff0000, v63
	v_lshlrev_b32_e32 v50, 16, v62
	v_mov_b32_e32 v62, v80
	v_mov_b32_e32 v63, v84
	s_waitcnt vmcnt(13)
	v_lshlrev_b32_e32 v96, 16, v69
	v_and_b32_e32 v97, 0xffff0000, v69
	v_lshlrev_b32_e32 v98, 16, v68
	v_and_b32_e32 v99, 0xffff0000, v68
	v_mov_b32_e32 v68, v87
	v_mov_b32_e32 v69, v57
	v_pk_mul_f32 v[90:91], v[90:91], v[90:91]
	v_mov_b32_e32 v110, v51
	v_mov_b32_e32 v111, v95
	v_pk_fma_f32 v[64:65], v[64:65], v[64:65], v[100:101]
	v_mov_b32_e32 v52, v78
	v_mov_b32_e32 v53, v82
	v_mov_b32_e32 v108, v50
	v_mov_b32_e32 v109, v94
	v_pk_fma_f32 v[62:63], v[62:63], v[62:63], v[90:91]
	v_pk_mul_f32 v[90:91], v[110:111], v[110:111]
	v_pk_fma_f32 v[64:65], v[68:69], v[68:69], v[64:65]
	s_waitcnt vmcnt(12)
	v_and_b32_e32 v69, 0xffff0000, v76
	v_mov_b32_e32 v54, v79
	v_mov_b32_e32 v55, v83
	v_mov_b32_e32 v104, v46
	v_mov_b32_e32 v105, v92
	v_pk_fma_f32 v[52:53], v[52:53], v[52:53], v[62:63]
	v_pk_fma_f32 v[62:63], v[108:109], v[108:109], v[90:91]
	v_lshlrev_b32_e32 v68, 16, v76
	v_mov_b32_e32 v102, v99
	v_mov_b32_e32 v103, v69
	v_pk_fma_f32 v[52:53], v[54:55], v[54:55], v[52:53]
	v_pk_fma_f32 v[54:55], v[104:105], v[104:105], v[62:63]
	v_lshlrev_b32_e32 v62, 16, v77
	v_mov_b32_e32 v100, v98
	v_mov_b32_e32 v101, v68
	v_pk_mul_f32 v[102:103], v[102:103], v[102:103]
	v_mov_b32_e32 v106, v47
	v_mov_b32_e32 v107, v93
	v_and_b32_e32 v63, 0xffff0000, v77
	v_mov_b32_e32 v76, v96
	v_mov_b32_e32 v77, v62
	v_pk_fma_f32 v[100:101], v[100:101], v[100:101], v[102:103]
	v_pk_fma_f32 v[54:55], v[106:107], v[106:107], v[54:55]
	v_mov_b32_e32 v90, v97
	v_mov_b32_e32 v91, v63
	v_pk_fma_f32 v[76:77], v[76:77], v[76:77], v[100:101]
	s_nop 0
	v_pk_fma_f32 v[76:77], v[90:91], v[90:91], v[76:77]
	v_mov_b32_e32 v90, v54
	v_mov_b32_e32 v91, v52
	v_mov_b32_e32 v52, v55
	v_pk_add_f32 v[52:53], v[90:91], v[52:53]
	v_mov_b32_e32 v54, v76
	v_mov_b32_e32 v55, v64
	v_pk_add_f32 v[52:53], v[52:53], v[54:55]
	v_mov_b32_e32 v64, v77
	v_pk_add_f32 v[52:53], v[52:53], v[64:65]
	ds_bpermute_b32 v55, v1, v53
	ds_bpermute_b32 v54, v1, v52
	s_waitcnt vmcnt(0)
	v_pk_add_f32 v[76:77], v[40:41], 1.0 op_sel_hi:[1,0]
	v_pk_add_f32 v[90:91], v[42:43], 1.0 op_sel_hi:[1,0]
	v_lshl_add_u64 v[64:65], v[26:27], 0, v[44:45]
	s_waitcnt lgkmcnt(0)
	v_pk_add_f32 v[52:53], v[52:53], v[54:55]
	ds_bpermute_b32 v55, v37, v53
	ds_bpermute_b32 v54, v37, v52
	s_waitcnt lgkmcnt(0)
	v_pk_add_f32 v[52:53], v[52:53], v[54:55]
	ds_bpermute_b32 v55, v70, v53
	ds_bpermute_b32 v54, v70, v52
	s_waitcnt lgkmcnt(0)
	v_pk_add_f32 v[52:53], v[52:53], v[54:55]
	ds_bpermute_b32 v55, v71, v53
	ds_bpermute_b32 v54, v71, v52
	s_waitcnt lgkmcnt(0)
	v_pk_add_f32 v[52:53], v[52:53], v[54:55]
	ds_bpermute_b32 v55, v72, v53
	ds_bpermute_b32 v54, v72, v52
	s_waitcnt lgkmcnt(0)
	v_pk_add_f32 v[52:53], v[52:53], v[54:55]
	ds_bpermute_b32 v55, v73, v53
	ds_bpermute_b32 v54, v73, v52
	s_waitcnt lgkmcnt(0)
	v_pk_add_f32 v[40:41], v[52:53], v[54:55]
	s_nop 0
	v_pk_fma_f32 v[52:53], v[40:41], s[24:25], v[36:37] op_sel_hi:[1,0,0]
	v_lshl_add_u64 v[54:55], v[48:49], 0, v[30:31]
	v_mul_f32_e32 v11, 0x4b800000, v53
	v_cmp_gt_f32_e32 vcc, s26, v53
	s_nop 1
	v_cndmask_b32_e32 v11, v53, v11, vcc
	v_rsq_f32_e32 v11, v11
	s_nop 0
	v_mul_f32_e32 v12, 0x45800000, v11
	v_cndmask_b32_e32 v12, v11, v12, vcc
	v_mul_f32_e32 v11, 0x4b800000, v52
	v_cmp_gt_f32_e32 vcc, s26, v52
	v_pk_mul_f32 v[40:41], v[12:13], v[80:81] op_sel_hi:[0,1]
	v_pk_mul_f32 v[40:41], v[2:3], v[40:41]
	v_cndmask_b32_e32 v11, v52, v11, vcc
	v_rsq_f32_e32 v11, v11
	v_pk_fma_f32 v[42:43], v[76:77], v[40:41], v[6:7]
	v_pk_mul_f32 v[40:41], v[12:13], v[78:79] op_sel_hi:[0,1]
	v_pk_mul_f32 v[40:41], v[4:5], v[40:41]
	v_mul_f32_e32 v39, 0x45800000, v11
	v_pk_fma_f32 v[40:41], v[90:91], v[40:41], v[8:9]
	v_cvt_pk_bf16_f32 v44, v42, v43
	v_cvt_pk_bf16_f32 v45, v40, v41
	v_cndmask_b32_e32 v120, v11, v39, vcc
	global_store_dwordx2 v[64:65], v[44:45], off
	v_pk_mul_f32 v[44:45], v[120:121], v[50:51] op_sel_hi:[0,1]
	v_pk_mul_f32 v[2:3], v[2:3], v[44:45]
	v_pk_mul_f32 v[80:81], v[120:121], v[94:95] op_sel_hi:[0,1]
	v_pk_fma_f32 v[6:7], v[76:77], v[2:3], v[6:7]
	v_pk_mul_f32 v[2:3], v[120:121], v[46:47] op_sel_hi:[0,1]
	v_pk_mul_f32 v[2:3], v[4:5], v[2:3]
	v_cvt_pk_bf16_f32 v4, v6, v7
	v_pk_fma_f32 v[2:3], v[90:91], v[2:3], v[8:9]
	v_pk_mul_f32 v[8:9], v[12:13], v[82:83] op_sel_hi:[0,1]
	v_cvt_pk_bf16_f32 v5, v2, v3
	global_store_dwordx2 v[66:67], v[4:5], off
	v_mov_b32_e32 v44, v200
	v_mov_b32_e32 v45, v201
	v_mov_b32_e32 v46, v202
	v_mov_b32_e32 v47, v203
	v_mov_b32_e32 v50, v204
	v_mov_b32_e32 v51, v205
	v_mov_b32_e32 v52, v206
	v_mov_b32_e32 v53, v207
	v_lshl_add_u64 v[4:5], v[60:61], 0, v[30:31]
	v_mov_b32_e32 v76, v208
	v_mov_b32_e32 v77, v209
	v_mov_b32_e32 v78, v210
	v_mov_b32_e32 v79, v211
	v_pk_mul_f32 v[4:5], v[12:13], v[84:85] op_sel_hi:[0,1]
	v_pk_mul_f32 v[82:83], v[120:121], v[92:93] op_sel_hi:[0,1]
	v_lshl_add_u64 v[54:55], v[48:49], 0, v[32:33]
	v_lshl_add_u64 v[84:85], v[48:49], 0, v[34:35]
	v_pk_mul_f32 v[48:49], v[12:13], v[88:89] op_sel_hi:[0,1]
	v_pk_mul_f32 v[88:89], v[120:121], v[96:97] op_sel_hi:[0,1]
	v_pk_mul_f32 v[58:59], v[12:13], v[58:59] op_sel_hi:[0,1]
	v_pk_mul_f32 v[56:57], v[12:13], v[56:57] op_sel_hi:[0,1]
	v_pk_mul_f32 v[62:63], v[120:121], v[62:63] op_sel_hi:[0,1]
	v_pk_mul_f32 v[4:5], v[44:45], v[4:5]
	v_pk_add_f32 v[50:51], v[50:51], 1.0 op_sel_hi:[1,0]
	v_pk_mul_f32 v[8:9], v[46:47], v[8:9]
	v_pk_add_f32 v[52:53], v[52:53], 1.0 op_sel_hi:[1,0]
	v_pk_mul_f32 v[80:81], v[44:45], v[80:81]
	v_pk_mul_f32 v[82:83], v[46:47], v[82:83]
	v_pk_fma_f32 v[46:47], v[4:5], v[50:51], v[76:77]
	v_pk_fma_f32 v[44:45], v[8:9], v[52:53], v[78:79]
	v_pk_fma_f32 v[8:9], v[50:51], v[80:81], v[76:77]
	v_pk_fma_f32 v[4:5], v[52:53], v[82:83], v[78:79]
	v_cvt_pk_bf16_f32 v50, v46, v47
	v_cvt_pk_bf16_f32 v51, v44, v45
	v_cvt_pk_bf16_f32 v52, v8, v9
	v_cvt_pk_bf16_f32 v53, v4, v5
	global_store_dwordx2 v[64:65], v[50:51], off offset:512
	global_store_dwordx2 v[66:67], v[52:53], off offset:512
	v_mov_b32_e32 v50, v212
	v_mov_b32_e32 v51, v213
	v_mov_b32_e32 v52, v214
	v_mov_b32_e32 v53, v215
	s_nop 0
	v_mov_b32_e32 v76, v216
	v_mov_b32_e32 v77, v217
	v_mov_b32_e32 v78, v218
	v_mov_b32_e32 v79, v219
	v_lshl_add_u64 v[54:55], v[60:61], 0, v[32:33]
	v_mov_b32_e32 v80, v220
	v_mov_b32_e32 v81, v221
	v_mov_b32_e32 v82, v222
	v_mov_b32_e32 v83, v223
	v_pk_mul_f32 v[54:55], v[12:13], v[86:87] op_sel_hi:[0,1]
	v_pk_mul_f32 v[86:87], v[120:121], v[98:99] op_sel_hi:[0,1]
	v_lshl_add_u64 v[60:61], v[60:61], 0, v[34:35]
	v_pk_mul_f32 v[48:49], v[48:49], v[50:51]
	v_pk_add_f32 v[76:77], v[76:77], 1.0 op_sel_hi:[1,0]
	v_pk_mul_f32 v[90:91], v[54:55], v[52:53]
	v_pk_add_f32 v[78:79], v[78:79], 1.0 op_sel_hi:[1,0]
	v_pk_mul_f32 v[50:51], v[86:87], v[50:51]
	v_pk_mul_f32 v[86:87], v[88:89], v[52:53]
	v_pk_fma_f32 v[54:55], v[48:49], v[76:77], v[80:81]
	v_pk_fma_f32 v[52:53], v[90:91], v[78:79], v[82:83]
	v_pk_fma_f32 v[50:51], v[50:51], v[76:77], v[80:81]
	v_pk_fma_f32 v[48:49], v[86:87], v[78:79], v[82:83]
	v_cvt_pk_bf16_f32 v76, v54, v55
	v_cvt_pk_bf16_f32 v77, v52, v53
	v_cvt_pk_bf16_f32 v78, v50, v51
	v_cvt_pk_bf16_f32 v79, v48, v49
	global_store_dwordx2 v[64:65], v[76:77], off offset:1024
	global_store_dwordx2 v[66:67], v[78:79], off offset:1024
	v_mov_b32_e32 v76, v224
	v_mov_b32_e32 v77, v225
	v_mov_b32_e32 v78, v226
	v_mov_b32_e32 v79, v227
	s_nop 0
	v_mov_b32_e32 v80, v228
	v_mov_b32_e32 v81, v229
	v_mov_b32_e32 v82, v230
	v_mov_b32_e32 v83, v231
	v_pk_mul_f32 v[58:59], v[58:59], v[76:77]
	v_mov_b32_e32 v84, v232
	v_mov_b32_e32 v85, v233
	v_mov_b32_e32 v86, v234
	v_mov_b32_e32 v87, v235
	ds_read_b128 v[88:91], v74
	ds_read_b128 v[92:95], v74 offset:1024
	ds_read_b128 v[96:99], v74 offset:2048
	ds_read_b128 v[100:103], v74 offset:3072
	ds_read_b128 v[104:107], v74 offset:7168
	ds_read_b128 v[108:111], v74 offset:6144
	ds_read_b128 v[112:115], v74 offset:5120
	ds_read_b128 v[116:119], v74 offset:4096
	s_waitcnt lgkmcnt(7)
	v_mul_f32_e32 v11, v43, v89
	v_mul_f32_e32 v12, v7, v89
	v_pk_mul_f32 v[60:61], v[120:121], v[68:69] op_sel_hi:[0,1]
	v_fmac_f32_e32 v11, v42, v88
	s_waitcnt lgkmcnt(0)
	v_mul_f32_e32 v39, v43, v117
	v_mul_f32_e32 v68, v7, v117
	v_fmac_f32_e32 v12, v6, v88
	v_fmac_f32_e32 v39, v42, v116
	v_fmac_f32_e32 v68, v6, v116
	v_fmac_f32_e32 v11, v40, v90
	v_fmac_f32_e32 v12, v2, v90
	v_mul_f32_e32 v69, v47, v93
	v_mul_f32_e32 v89, v47, v113
	v_mul_f32_e32 v90, v9, v113
	v_fmac_f32_e32 v39, v40, v118
	v_fmac_f32_e32 v68, v2, v118
	v_fmac_f32_e32 v69, v46, v92
	v_fmac_f32_e32 v89, v46, v112
	v_fmac_f32_e32 v90, v8, v112
	v_fmac_f32_e32 v11, v41, v91
	v_fmac_f32_e32 v39, v41, v119
	v_fmac_f32_e32 v68, v3, v119
	v_mul_f32_e32 v88, v9, v93
	v_fmac_f32_e32 v69, v44, v94
	v_fmac_f32_e32 v89, v44, v114
	v_fmac_f32_e32 v90, v4, v114
	v_add_f32_e32 v11, 0, v11
	v_add_f32_e32 v39, 0, v39
	v_add_f32_e32 v68, 0, v68
	v_fmac_f32_e32 v88, v8, v92
	v_fmac_f32_e32 v69, v45, v95
	v_fmac_f32_e32 v89, v45, v115
	v_fmac_f32_e32 v90, v5, v115
	v_fmac_f32_e32 v12, v3, v91
	v_fmac_f32_e32 v88, v4, v94
	v_add_f32_e32 v11, v11, v69
	v_add_f32_e32 v39, v89, v39
	v_add_f32_e32 v68, v90, v68
	v_mul_f32_e32 v69, v55, v97
	v_mul_f32_e32 v89, v55, v109
	v_mul_f32_e32 v90, v51, v109
	v_add_f32_e32 v12, 0, v12
	v_fmac_f32_e32 v88, v5, v95
	v_fmac_f32_e32 v69, v54, v96
	v_fmac_f32_e32 v89, v54, v108
	v_fmac_f32_e32 v90, v50, v108
	v_add_f32_e32 v12, v12, v88
	v_mul_f32_e32 v88, v51, v97
	v_fmac_f32_e32 v69, v52, v98
	v_fmac_f32_e32 v89, v52, v110
	v_fmac_f32_e32 v90, v48, v110
	v_fmac_f32_e32 v88, v50, v96
	v_fmac_f32_e32 v69, v53, v99
	v_fmac_f32_e32 v89, v53, v111
	v_fmac_f32_e32 v90, v49, v111
	v_fmac_f32_e32 v88, v48, v98
	v_add_f32_e32 v11, v11, v69
	v_add_f32_e32 v39, v89, v39
	v_add_f32_e32 v89, v90, v68
	v_pk_add_f32 v[68:69], v[80:81], 1.0 op_sel_hi:[1,0]
	v_pk_mul_f32 v[76:77], v[60:61], v[76:77]
	v_fmac_f32_e32 v88, v49, v99
	v_pk_mul_f32 v[56:57], v[56:57], v[78:79]
	v_pk_add_f32 v[80:81], v[82:83], 1.0 op_sel_hi:[1,0]
	v_pk_mul_f32 v[78:79], v[62:63], v[78:79]
	v_add_f32_e32 v88, v12, v88
	v_pk_fma_f32 v[62:63], v[58:59], v[68:69], v[84:85]
	v_pk_fma_f32 v[58:59], v[76:77], v[68:69], v[84:85]
	v_pk_fma_f32 v[60:61], v[56:57], v[80:81], v[86:87]
	v_pk_fma_f32 v[56:57], v[78:79], v[80:81], v[86:87]
	v_mul_f32_e32 v12, v63, v101
	v_mul_f32_e32 v78, v59, v101
	v_mul_f32_e32 v79, v63, v105
	v_mul_f32_e32 v80, v59, v105
	v_fmac_f32_e32 v12, v62, v100
	v_fmac_f32_e32 v78, v58, v100
	v_fmac_f32_e32 v79, v62, v104
	v_fmac_f32_e32 v80, v58, v104
	v_fmac_f32_e32 v12, v60, v102
	v_fmac_f32_e32 v78, v56, v102
	v_fmac_f32_e32 v79, v60, v106
	v_fmac_f32_e32 v80, v56, v106
	v_cvt_pk_bf16_f32 v68, v62, v63
	v_cvt_pk_bf16_f32 v69, v60, v61
	v_fmac_f32_e32 v12, v61, v103
	v_fmac_f32_e32 v78, v57, v103
	v_fmac_f32_e32 v79, v61, v107
	v_fmac_f32_e32 v80, v57, v107
	v_cvt_pk_bf16_f32 v76, v58, v59
	v_cvt_pk_bf16_f32 v77, v56, v57
	global_store_dwordx2 v[64:65], v[68:69], off offset:1536
	global_store_dwordx2 v[66:67], v[76:77], off offset:1536
	v_add_f32_e32 v12, v11, v12
	v_add_f32_e32 v64, v88, v78
	v_add_f32_e32 v11, v79, v39
	v_add_f32_e32 v39, v80, v89
	ds_read_b128 v[66:69], v74 offset:8192
	ds_read_b128 v[76:79], v74 offset:9216
	s_waitcnt lgkmcnt(1)
	v_mul_f32_e32 v65, v43, v67
	v_mul_f32_e32 v67, v7, v67
	v_fmac_f32_e32 v65, v42, v66
	v_fmac_f32_e32 v67, v6, v66
	s_waitcnt lgkmcnt(0)
	v_mul_f32_e32 v66, v47, v77
	v_fmac_f32_e32 v65, v40, v68
	v_fmac_f32_e32 v66, v46, v76
	v_fmac_f32_e32 v67, v2, v68
	v_fmac_f32_e32 v65, v41, v69
	v_fmac_f32_e32 v66, v44, v78
	v_add_f32_e32 v65, 0, v65
	v_fmac_f32_e32 v67, v3, v69
	v_fmac_f32_e32 v66, v45, v79
	v_add_f32_e32 v80, 0, v67
	v_add_f32_e32 v65, v65, v66
	v_mul_f32_e32 v77, v9, v77
	ds_read_b128 v[66:69], v74 offset:10240
	v_fmac_f32_e32 v77, v8, v76
	v_fmac_f32_e32 v77, v4, v78
	v_fmac_f32_e32 v77, v5, v79
	v_add_f32_e32 v80, v80, v77
	ds_read_b128 v[76:79], v74 offset:11264
	s_waitcnt lgkmcnt(1)
	v_mul_f32_e32 v81, v55, v67
	v_mul_f32_e32 v67, v51, v67
	v_fmac_f32_e32 v67, v50, v66
	v_fmac_f32_e32 v67, v48, v68
	v_fmac_f32_e32 v67, v49, v69
	v_fmac_f32_e32 v81, v54, v66
	v_add_f32_e32 v66, v80, v67
	s_waitcnt lgkmcnt(0)
	v_mul_f32_e32 v67, v63, v77
	v_fmac_f32_e32 v81, v52, v68
	v_fmac_f32_e32 v67, v62, v76
	v_fmac_f32_e32 v81, v53, v69
	v_fmac_f32_e32 v67, v60, v78
	v_add_f32_e32 v65, v65, v81
	v_fmac_f32_e32 v67, v61, v79
	ds_read_b128 v[80:83], v74 offset:13312
	ds_read_b128 v[84:87], v74 offset:12288
	v_add_f32_e32 v65, v65, v67
	v_mul_f32_e32 v67, v59, v77
	v_fmac_f32_e32 v67, v58, v76
	v_fmac_f32_e32 v67, v56, v78
	v_fmac_f32_e32 v67, v57, v79
	v_add_f32_e32 v66, v66, v67
	s_waitcnt lgkmcnt(0)
	v_mul_f32_e32 v67, v43, v85
	v_fmac_f32_e32 v67, v42, v84
	v_mul_f32_e32 v69, v47, v81
	v_fmac_f32_e32 v67, v40, v86
	v_fmac_f32_e32 v69, v46, v80
	v_fmac_f32_e32 v67, v41, v87
	v_fmac_f32_e32 v69, v44, v82
	ds_read_b128 v[76:79], v74 offset:15360
	ds_read_b128 v[88:91], v74 offset:14336
	v_add_f32_e32 v67, 0, v67
	v_mul_f32_e32 v68, v7, v85
	v_fmac_f32_e32 v69, v45, v83
	v_fmac_f32_e32 v68, v6, v84
	v_add_f32_e32 v67, v69, v67
	v_mul_f32_e32 v69, v9, v81
	v_fmac_f32_e32 v68, v2, v86
	v_fmac_f32_e32 v69, v8, v80
	v_fmac_f32_e32 v68, v3, v87
	v_fmac_f32_e32 v69, v4, v82
	v_add_f32_e32 v68, 0, v68
	v_fmac_f32_e32 v69, v5, v83
	v_add_f32_e32 v68, v69, v68
	s_waitcnt lgkmcnt(0)
	v_mul_f32_e32 v69, v55, v89
	v_fmac_f32_e32 v69, v54, v88
	v_fmac_f32_e32 v69, v52, v90
	v_fmac_f32_e32 v69, v53, v91
	v_add_f32_e32 v67, v69, v67
	v_mul_f32_e32 v69, v51, v89
	v_fmac_f32_e32 v69, v50, v88
	v_fmac_f32_e32 v69, v48, v90
	v_fmac_f32_e32 v69, v49, v91
	v_add_f32_e32 v68, v69, v68
	v_mul_f32_e32 v69, v63, v77
	v_fmac_f32_e32 v69, v62, v76
	v_fmac_f32_e32 v69, v60, v78
	v_fmac_f32_e32 v69, v61, v79
	v_add_f32_e32 v67, v69, v67
	v_mul_f32_e32 v69, v59, v77
	v_fmac_f32_e32 v69, v58, v76
	v_fmac_f32_e32 v69, v56, v78
	v_fmac_f32_e32 v69, v57, v79
	v_add_f32_e32 v68, v69, v68
	ds_read_b128 v[76:79], v74 offset:16384
	ds_read_b128 v[80:83], v74 offset:17408
	s_waitcnt lgkmcnt(1)
	v_mul_f32_e32 v69, v43, v77
	v_mul_f32_e32 v77, v7, v77
	v_fmac_f32_e32 v69, v42, v76
	v_fmac_f32_e32 v77, v6, v76
	s_waitcnt lgkmcnt(0)
	v_mul_f32_e32 v76, v47, v81
	v_fmac_f32_e32 v69, v40, v78
	v_fmac_f32_e32 v76, v46, v80
	v_fmac_f32_e32 v77, v2, v78
	v_fmac_f32_e32 v69, v41, v79
	v_fmac_f32_e32 v76, v44, v82
	v_add_f32_e32 v69, 0, v69
	v_fmac_f32_e32 v77, v3, v79
	v_fmac_f32_e32 v76, v45, v83
	v_add_f32_e32 v84, 0, v77
	v_add_f32_e32 v69, v69, v76
	v_mul_f32_e32 v81, v9, v81
	ds_read_b128 v[76:79], v74 offset:18432
	v_fmac_f32_e32 v81, v8, v80
	v_fmac_f32_e32 v81, v4, v82
	v_fmac_f32_e32 v81, v5, v83
	v_add_f32_e32 v84, v84, v81
	ds_read_b128 v[80:83], v74 offset:19456
	s_waitcnt lgkmcnt(1)
	v_mul_f32_e32 v85, v55, v77
	v_mul_f32_e32 v77, v51, v77
	v_fmac_f32_e32 v77, v50, v76
	v_fmac_f32_e32 v77, v48, v78
	v_fmac_f32_e32 v77, v49, v79
	v_fmac_f32_e32 v85, v54, v76
	v_add_f32_e32 v76, v84, v77
	s_waitcnt lgkmcnt(0)
	v_mul_f32_e32 v77, v63, v81
	v_fmac_f32_e32 v85, v52, v78
	v_fmac_f32_e32 v77, v62, v80
	v_fmac_f32_e32 v85, v53, v79
	v_fmac_f32_e32 v77, v60, v82
	v_add_f32_e32 v69, v69, v85
	v_fmac_f32_e32 v77, v61, v83
	v_add_f32_e32 v69, v69, v77
	v_mul_f32_e32 v77, v59, v81
	v_fmac_f32_e32 v77, v58, v80
	ds_read_b128 v[78:81], v74 offset:21504
	ds_read_b128 v[84:87], v74 offset:20480
	v_fmac_f32_e32 v77, v56, v82
	ds_read_b128 v[88:91], v74 offset:23552
	ds_read_b128 v[92:95], v74 offset:22528
	v_fmac_f32_e32 v77, v57, v83
	s_waitcnt lgkmcnt(3)
	v_mul_f32_e32 v83, v47, v79
	s_waitcnt lgkmcnt(2)
	v_mul_f32_e32 v82, v7, v85
	v_fmac_f32_e32 v82, v6, v84
	v_mul_f32_e32 v79, v9, v79
	v_fmac_f32_e32 v82, v2, v86
	v_fmac_f32_e32 v79, v8, v78
	v_add_f32_e32 v76, v76, v77
	v_mul_f32_e32 v77, v43, v85
	v_fmac_f32_e32 v82, v3, v87
	v_fmac_f32_e32 v79, v4, v80
	v_fmac_f32_e32 v77, v42, v84
	v_add_f32_e32 v82, 0, v82
	v_fmac_f32_e32 v79, v5, v81
	v_fmac_f32_e32 v77, v40, v86
	v_fmac_f32_e32 v83, v46, v78
	v_add_f32_e32 v78, v79, v82
	s_waitcnt lgkmcnt(0)
	v_mul_f32_e32 v79, v55, v93
	v_fmac_f32_e32 v77, v41, v87
	v_fmac_f32_e32 v83, v44, v80
	v_fmac_f32_e32 v79, v54, v92
	v_add_f32_e32 v77, 0, v77
	v_fmac_f32_e32 v83, v45, v81
	v_fmac_f32_e32 v79, v52, v94
	v_add_f32_e32 v77, v83, v77
	v_fmac_f32_e32 v79, v53, v95
	v_add_f32_e32 v77, v79, v77
	v_mul_f32_e32 v79, v51, v93
	v_fmac_f32_e32 v79, v50, v92
	v_fmac_f32_e32 v79, v48, v94
	v_fmac_f32_e32 v79, v49, v95
	v_add_f32_e32 v78, v79, v78
	v_mul_f32_e32 v79, v63, v89
	v_fmac_f32_e32 v79, v62, v88
	v_fmac_f32_e32 v79, v60, v90
	v_fmac_f32_e32 v79, v61, v91
	v_add_f32_e32 v77, v79, v77
	v_mul_f32_e32 v79, v59, v89
	v_fmac_f32_e32 v79, v58, v88
	v_fmac_f32_e32 v79, v56, v90
	v_fmac_f32_e32 v79, v57, v91
	v_add_f32_e32 v78, v79, v78
	ds_read_b128 v[80:83], v74 offset:24576
	ds_read_b128 v[84:87], v74 offset:25600
	s_waitcnt lgkmcnt(1)
	v_mul_f32_e32 v79, v43, v81
	v_mul_f32_e32 v81, v7, v81
	v_fmac_f32_e32 v79, v42, v80
	v_fmac_f32_e32 v81, v6, v80
	s_waitcnt lgkmcnt(0)
	v_mul_f32_e32 v80, v47, v85
	v_fmac_f32_e32 v79, v40, v82
	v_fmac_f32_e32 v80, v46, v84
	v_fmac_f32_e32 v81, v2, v82
	v_fmac_f32_e32 v79, v41, v83
	v_fmac_f32_e32 v80, v44, v86
	v_add_f32_e32 v79, 0, v79
	v_fmac_f32_e32 v81, v3, v83
	v_fmac_f32_e32 v80, v45, v87
	v_add_f32_e32 v88, 0, v81
	v_add_f32_e32 v79, v79, v80
	v_mul_f32_e32 v85, v9, v85
	ds_read_b128 v[80:83], v74 offset:26624
	v_fmac_f32_e32 v85, v8, v84
	v_fmac_f32_e32 v85, v4, v86
	v_fmac_f32_e32 v85, v5, v87
	v_add_f32_e32 v88, v88, v85
	ds_read_b128 v[84:87], v74 offset:27648
	s_waitcnt lgkmcnt(1)
	v_mul_f32_e32 v89, v55, v81
	v_mul_f32_e32 v81, v51, v81
	v_fmac_f32_e32 v81, v50, v80
	v_fmac_f32_e32 v81, v48, v82
	v_fmac_f32_e32 v81, v49, v83
	v_fmac_f32_e32 v89, v54, v80
	v_add_f32_e32 v80, v88, v81
	s_waitcnt lgkmcnt(0)
	v_mul_f32_e32 v81, v63, v85
	v_fmac_f32_e32 v89, v52, v82
	v_fmac_f32_e32 v81, v62, v84
	v_fmac_f32_e32 v89, v53, v83
	v_fmac_f32_e32 v81, v60, v86
	v_add_f32_e32 v79, v79, v89
	v_fmac_f32_e32 v81, v61, v87
	v_add_f32_e32 v79, v79, v81
	v_mul_f32_e32 v81, v59, v85
	v_fmac_f32_e32 v81, v58, v84
	ds_read_b128 v[82:85], v74 offset:29696
	ds_read_b128 v[88:91], v74 offset:28672
	v_fmac_f32_e32 v81, v56, v86
	ds_read_b128 v[92:95], v74 offset:31744
	ds_read_b128 v[96:99], v74 offset:30720
	v_fmac_f32_e32 v81, v57, v87
	s_waitcnt lgkmcnt(3)
	v_mul_f32_e32 v87, v47, v83
	s_waitcnt lgkmcnt(2)
	v_mul_f32_e32 v86, v7, v89
	v_fmac_f32_e32 v86, v6, v88
	v_mul_f32_e32 v83, v9, v83
	v_fmac_f32_e32 v86, v2, v90
	v_fmac_f32_e32 v83, v8, v82
	v_add_f32_e32 v80, v80, v81
	v_mul_f32_e32 v81, v43, v89
	v_fmac_f32_e32 v86, v3, v91
	v_fmac_f32_e32 v83, v4, v84
	v_fmac_f32_e32 v81, v42, v88
	v_add_f32_e32 v86, 0, v86
	v_fmac_f32_e32 v83, v5, v85
	v_fmac_f32_e32 v81, v40, v90
	v_fmac_f32_e32 v87, v46, v82
	v_add_f32_e32 v82, v83, v86
	s_waitcnt lgkmcnt(0)
	v_mul_f32_e32 v83, v55, v97
	v_fmac_f32_e32 v81, v41, v91
	v_fmac_f32_e32 v87, v44, v84
	v_fmac_f32_e32 v83, v54, v96
	v_add_f32_e32 v81, 0, v81
	v_fmac_f32_e32 v87, v45, v85
	v_fmac_f32_e32 v83, v52, v98
	v_add_f32_e32 v81, v87, v81
	v_fmac_f32_e32 v83, v53, v99
	v_add_f32_e32 v81, v83, v81
	v_mul_f32_e32 v83, v51, v97
	v_fmac_f32_e32 v83, v50, v96
	v_fmac_f32_e32 v83, v48, v98
	v_fmac_f32_e32 v83, v49, v99
	v_add_f32_e32 v82, v83, v82
	v_mul_f32_e32 v83, v63, v93
	v_fmac_f32_e32 v83, v62, v92
	v_fmac_f32_e32 v83, v60, v94
	v_fmac_f32_e32 v83, v61, v95
	v_add_f32_e32 v81, v83, v81
	v_mul_f32_e32 v83, v59, v93
	v_fmac_f32_e32 v83, v58, v92
	v_fmac_f32_e32 v83, v56, v94
	v_fmac_f32_e32 v83, v57, v95
	v_add_f32_e32 v82, v83, v82
	ds_read_b128 v[84:87], v74 offset:32768
	ds_read_b128 v[88:91], v74 offset:33792
	s_waitcnt lgkmcnt(1)
	v_mul_f32_e32 v83, v43, v85
	v_mul_f32_e32 v85, v7, v85
	v_fmac_f32_e32 v83, v42, v84
	v_fmac_f32_e32 v85, v6, v84
	s_waitcnt lgkmcnt(0)
	v_mul_f32_e32 v84, v47, v89
	v_fmac_f32_e32 v83, v40, v86
	v_fmac_f32_e32 v84, v46, v88
	v_fmac_f32_e32 v85, v2, v86
	v_fmac_f32_e32 v83, v41, v87
	v_fmac_f32_e32 v84, v44, v90
	v_add_f32_e32 v83, 0, v83
	v_fmac_f32_e32 v85, v3, v87
	v_fmac_f32_e32 v84, v45, v91
	v_add_f32_e32 v92, 0, v85
	v_add_f32_e32 v83, v83, v84
	v_mul_f32_e32 v89, v9, v89
	ds_read_b128 v[84:87], v74 offset:34816
	v_fmac_f32_e32 v89, v8, v88
	v_fmac_f32_e32 v89, v4, v90
	v_fmac_f32_e32 v89, v5, v91
	v_add_f32_e32 v92, v92, v89
	ds_read_b128 v[88:91], v74 offset:35840
	s_waitcnt lgkmcnt(1)
	v_mul_f32_e32 v93, v55, v85
	v_mul_f32_e32 v85, v51, v85
	v_fmac_f32_e32 v85, v50, v84
	v_fmac_f32_e32 v85, v48, v86
	v_fmac_f32_e32 v85, v49, v87
	v_fmac_f32_e32 v93, v54, v84
	v_add_f32_e32 v84, v92, v85
	s_waitcnt lgkmcnt(0)
	v_mul_f32_e32 v85, v63, v89
	v_fmac_f32_e32 v93, v52, v86
	v_fmac_f32_e32 v85, v62, v88
	v_fmac_f32_e32 v93, v53, v87
	v_fmac_f32_e32 v85, v60, v90
	v_add_f32_e32 v83, v83, v93
	v_fmac_f32_e32 v85, v61, v91
	v_add_f32_e32 v83, v83, v85
	v_mul_f32_e32 v85, v59, v89
	v_fmac_f32_e32 v85, v58, v88
	ds_read_b128 v[86:89], v74 offset:37888
	ds_read_b128 v[92:95], v74 offset:36864
	v_fmac_f32_e32 v85, v56, v90
	ds_read_b128 v[96:99], v74 offset:39936
	ds_read_b128 v[100:103], v74 offset:38912
	v_fmac_f32_e32 v85, v57, v91
	s_waitcnt lgkmcnt(3)
	v_mul_f32_e32 v91, v47, v87
	s_waitcnt lgkmcnt(2)
	v_mul_f32_e32 v90, v7, v93
	v_fmac_f32_e32 v90, v6, v92
	v_mul_f32_e32 v87, v9, v87
	v_fmac_f32_e32 v90, v2, v94
	v_fmac_f32_e32 v87, v8, v86
	v_add_f32_e32 v84, v84, v85
	v_mul_f32_e32 v85, v43, v93
	v_fmac_f32_e32 v90, v3, v95
	v_fmac_f32_e32 v87, v4, v88
	v_fmac_f32_e32 v85, v42, v92
	v_add_f32_e32 v90, 0, v90
	v_fmac_f32_e32 v87, v5, v89
	v_fmac_f32_e32 v85, v40, v94
	v_fmac_f32_e32 v91, v46, v86
	v_add_f32_e32 v86, v87, v90
	s_waitcnt lgkmcnt(0)
	v_mul_f32_e32 v87, v55, v101
	v_fmac_f32_e32 v85, v41, v95
	v_fmac_f32_e32 v91, v44, v88
	v_fmac_f32_e32 v87, v54, v100
	v_add_f32_e32 v85, 0, v85
	v_fmac_f32_e32 v91, v45, v89
	v_fmac_f32_e32 v87, v52, v102
	v_add_f32_e32 v85, v91, v85
	v_fmac_f32_e32 v87, v53, v103
	v_add_f32_e32 v85, v87, v85
	v_mul_f32_e32 v87, v51, v101
	v_fmac_f32_e32 v87, v50, v100
	v_fmac_f32_e32 v87, v48, v102
	v_fmac_f32_e32 v87, v49, v103
	v_add_f32_e32 v86, v87, v86
	v_mul_f32_e32 v87, v63, v97
	v_fmac_f32_e32 v87, v62, v96
	v_fmac_f32_e32 v87, v60, v98
	v_fmac_f32_e32 v87, v61, v99
	v_add_f32_e32 v85, v87, v85
	v_mul_f32_e32 v87, v59, v97
	v_fmac_f32_e32 v87, v58, v96
	v_fmac_f32_e32 v87, v56, v98
	v_fmac_f32_e32 v87, v57, v99
	v_add_f32_e32 v86, v87, v86
	ds_read_b128 v[88:91], v74 offset:40960
	ds_read_b128 v[92:95], v74 offset:41984
	s_waitcnt lgkmcnt(1)
	v_mul_f32_e32 v87, v43, v89
	v_mul_f32_e32 v89, v7, v89
	v_fmac_f32_e32 v87, v42, v88
	v_fmac_f32_e32 v89, v6, v88
	s_waitcnt lgkmcnt(0)
	v_mul_f32_e32 v88, v47, v93
	v_fmac_f32_e32 v87, v40, v90
	v_fmac_f32_e32 v88, v46, v92
	v_mul_f32_e32 v93, v9, v93
	v_fmac_f32_e32 v89, v2, v90
	v_fmac_f32_e32 v87, v41, v91
	v_fmac_f32_e32 v88, v44, v94
	v_fmac_f32_e32 v93, v8, v92
	v_add_f32_e32 v87, 0, v87
	v_fmac_f32_e32 v89, v3, v91
	v_fmac_f32_e32 v88, v45, v95
	v_fmac_f32_e32 v93, v4, v94
	v_add_f32_e32 v96, 0, v89
	v_add_f32_e32 v87, v87, v88
	ds_read_b128 v[88:91], v74 offset:43008
	v_fmac_f32_e32 v93, v5, v95
	v_add_f32_e32 v96, v96, v93
	ds_read_b128 v[92:95], v74 offset:44032
	s_waitcnt lgkmcnt(1)
	v_mul_f32_e32 v97, v55, v89
	v_mul_f32_e32 v89, v51, v89
	v_fmac_f32_e32 v97, v54, v88
	v_fmac_f32_e32 v89, v50, v88
	s_waitcnt lgkmcnt(0)
	v_mul_f32_e32 v88, v63, v93
	v_fmac_f32_e32 v97, v52, v90
	v_fmac_f32_e32 v88, v62, v92
	v_fmac_f32_e32 v97, v53, v91
	v_fmac_f32_e32 v89, v48, v90
	v_fmac_f32_e32 v88, v60, v94
	v_add_f32_e32 v87, v87, v97
	v_fmac_f32_e32 v89, v49, v91
	v_fmac_f32_e32 v88, v61, v95
	v_add_f32_e32 v100, v96, v89
	v_add_f32_e32 v87, v87, v88
	ds_read_b128 v[88:91], v74 offset:46080
	ds_read_b128 v[96:99], v74 offset:45056
	v_mul_f32_e32 v93, v59, v93
	v_fmac_f32_e32 v93, v58, v92
	v_fmac_f32_e32 v93, v56, v94
	v_fmac_f32_e32 v93, v57, v95
	s_waitcnt lgkmcnt(0)
	v_mul_f32_e32 v105, v43, v97
	v_mul_f32_e32 v97, v7, v97
	v_add_f32_e32 v104, v100, v93
	ds_read_b128 v[92:95], v74 offset:48128
	ds_read_b128 v[100:103], v74 offset:47104
	v_fmac_f32_e32 v97, v6, v96
	v_fmac_f32_e32 v97, v2, v98
	v_fmac_f32_e32 v97, v3, v99
	v_fmac_f32_e32 v105, v42, v96
	v_add_f32_e32 v96, 0, v97
	v_mul_f32_e32 v97, v47, v89
	v_mul_f32_e32 v89, v9, v89
	v_fmac_f32_e32 v97, v46, v88
	v_fmac_f32_e32 v89, v8, v88
	v_fmac_f32_e32 v97, v44, v90
	v_fmac_f32_e32 v89, v4, v90
	s_waitcnt lgkmcnt(0)
	v_mul_f32_e32 v90, v51, v101
	v_fmac_f32_e32 v90, v50, v100
	v_fmac_f32_e32 v89, v5, v91
	v_fmac_f32_e32 v90, v48, v102
	v_fmac_f32_e32 v105, v40, v98
	v_add_f32_e32 v88, v89, v96
	v_mul_f32_e32 v89, v55, v101
	v_fmac_f32_e32 v90, v49, v103
	v_fmac_f32_e32 v105, v41, v99
	v_fmac_f32_e32 v89, v54, v100
	v_add_f32_e32 v88, v90, v88
	v_mul_f32_e32 v90, v63, v93
	v_add_f32_e32 v105, 0, v105
	v_fmac_f32_e32 v97, v45, v91
	v_fmac_f32_e32 v89, v52, v102
	v_fmac_f32_e32 v90, v62, v92
	v_add_f32_e32 v97, v97, v105
	v_fmac_f32_e32 v89, v53, v103
	v_fmac_f32_e32 v90, v60, v94
	v_add_f32_e32 v89, v89, v97
	v_fmac_f32_e32 v90, v61, v95
	v_add_f32_e32 v105, v90, v89
	v_mul_f32_e32 v89, v59, v93
	v_fmac_f32_e32 v89, v58, v92
	v_fmac_f32_e32 v89, v56, v94
	v_fmac_f32_e32 v89, v57, v95
	v_add_f32_e32 v106, v89, v88
	ds_read_b128 v[88:91], v74 offset:49152
	ds_read_b128 v[92:95], v74 offset:50176
	s_waitcnt lgkmcnt(1)
	v_mul_f32_e32 v96, v43, v89
	v_mul_f32_e32 v89, v7, v89
	v_fmac_f32_e32 v96, v42, v88
	v_fmac_f32_e32 v89, v6, v88
	v_fmac_f32_e32 v96, v40, v90
	v_fmac_f32_e32 v89, v2, v90
	v_fmac_f32_e32 v96, v41, v91
	v_fmac_f32_e32 v89, v3, v91
	v_add_f32_e32 v88, 0, v96
	v_add_f32_e32 v96, 0, v89
	s_waitcnt lgkmcnt(0)
	v_mul_f32_e32 v89, v47, v93
	v_fmac_f32_e32 v89, v46, v92
	v_mul_f32_e32 v93, v9, v93
	v_fmac_f32_e32 v89, v44, v94
	v_fmac_f32_e32 v93, v8, v92
	v_fmac_f32_e32 v89, v45, v95
	v_fmac_f32_e32 v93, v4, v94
	v_add_f32_e32 v97, v88, v89
	ds_read_b128 v[88:91], v74 offset:51200
	v_fmac_f32_e32 v93, v5, v95
	v_add_f32_e32 v96, v96, v93
	ds_read_b128 v[92:95], v74 offset:52224
	s_waitcnt lgkmcnt(1)
	v_mul_f32_e32 v98, v55, v89
	v_mul_f32_e32 v89, v51, v89
	v_fmac_f32_e32 v98, v54, v88
	v_fmac_f32_e32 v89, v50, v88
	s_waitcnt lgkmcnt(0)
	v_mul_f32_e32 v88, v63, v93
	v_fmac_f32_e32 v98, v52, v90
	v_fmac_f32_e32 v88, v62, v92
	v_fmac_f32_e32 v98, v53, v91
	v_fmac_f32_e32 v89, v48, v90
	v_fmac_f32_e32 v88, v60, v94
	v_add_f32_e32 v97, v97, v98
	v_fmac_f32_e32 v89, v49, v91
	v_fmac_f32_e32 v88, v61, v95
	v_add_f32_e32 v100, v96, v89
	v_add_f32_e32 v107, v97, v88
	ds_read_b128 v[88:91], v74 offset:54272
	ds_read_b128 v[96:99], v74 offset:53248
	v_mul_f32_e32 v93, v59, v93
	v_fmac_f32_e32 v93, v58, v92
	v_fmac_f32_e32 v93, v56, v94
	v_fmac_f32_e32 v93, v57, v95
	s_waitcnt lgkmcnt(0)
	v_mul_f32_e32 v109, v43, v97
	v_mul_f32_e32 v97, v7, v97
	v_add_f32_e32 v108, v100, v93
	ds_read_b128 v[92:95], v74 offset:56320
	ds_read_b128 v[100:103], v74 offset:55296
	v_fmac_f32_e32 v97, v6, v96
	v_fmac_f32_e32 v97, v2, v98
	v_fmac_f32_e32 v97, v3, v99
	v_fmac_f32_e32 v109, v42, v96
	v_add_f32_e32 v96, 0, v97
	v_mul_f32_e32 v97, v47, v89
	v_mul_f32_e32 v89, v9, v89
	v_fmac_f32_e32 v97, v46, v88
	v_fmac_f32_e32 v89, v8, v88
	v_fmac_f32_e32 v97, v44, v90
	v_fmac_f32_e32 v89, v4, v90
	s_waitcnt lgkmcnt(0)
	v_mul_f32_e32 v90, v51, v101
	v_fmac_f32_e32 v90, v50, v100
	v_fmac_f32_e32 v89, v5, v91
	v_fmac_f32_e32 v90, v48, v102
	v_fmac_f32_e32 v109, v40, v98
	v_add_f32_e32 v88, v89, v96
	v_mul_f32_e32 v89, v55, v101
	v_fmac_f32_e32 v90, v49, v103
	v_fmac_f32_e32 v109, v41, v99
	v_fmac_f32_e32 v89, v54, v100
	v_add_f32_e32 v88, v90, v88
	v_mul_f32_e32 v90, v63, v93
	v_add_f32_e32 v109, 0, v109
	v_fmac_f32_e32 v97, v45, v91
	v_fmac_f32_e32 v89, v52, v102
	v_fmac_f32_e32 v90, v62, v92
	v_add_f32_e32 v97, v97, v109
	v_fmac_f32_e32 v89, v53, v103
	v_fmac_f32_e32 v90, v60, v94
	v_add_f32_e32 v89, v89, v97
	v_fmac_f32_e32 v90, v61, v95
	v_add_f32_e32 v109, v90, v89
	v_mul_f32_e32 v89, v59, v93
	v_fmac_f32_e32 v89, v58, v92
	v_fmac_f32_e32 v89, v56, v94
	v_fmac_f32_e32 v89, v57, v95
	v_add_f32_e32 v110, v89, v88
	ds_read_b128 v[88:91], v74 offset:57344
	ds_read_b128 v[92:95], v74 offset:58368
	s_waitcnt lgkmcnt(1)
	v_mul_f32_e32 v96, v43, v89
	v_mul_f32_e32 v89, v7, v89
	v_fmac_f32_e32 v96, v42, v88
	v_fmac_f32_e32 v89, v6, v88
	v_fmac_f32_e32 v96, v40, v90
	v_fmac_f32_e32 v89, v2, v90
	v_fmac_f32_e32 v96, v41, v91
	v_fmac_f32_e32 v89, v3, v91
	v_add_f32_e32 v88, 0, v96
	v_add_f32_e32 v96, 0, v89
	s_waitcnt lgkmcnt(0)
	v_mul_f32_e32 v89, v47, v93
	v_fmac_f32_e32 v89, v46, v92
	v_mul_f32_e32 v93, v9, v93
	v_fmac_f32_e32 v89, v44, v94
	v_fmac_f32_e32 v93, v8, v92
	v_fmac_f32_e32 v89, v45, v95
	v_fmac_f32_e32 v93, v4, v94
	v_add_f32_e32 v97, v88, v89
	ds_read_b128 v[88:91], v74 offset:59392
	v_fmac_f32_e32 v93, v5, v95
	v_add_f32_e32 v96, v96, v93
	ds_read_b128 v[92:95], v74 offset:60416
	s_waitcnt lgkmcnt(1)
	v_mul_f32_e32 v98, v55, v89
	v_mul_f32_e32 v89, v51, v89
	v_fmac_f32_e32 v98, v54, v88
	v_fmac_f32_e32 v89, v50, v88
	s_waitcnt lgkmcnt(0)
	v_mul_f32_e32 v88, v63, v93
	v_fmac_f32_e32 v98, v52, v90
	v_fmac_f32_e32 v88, v62, v92
	v_fmac_f32_e32 v98, v53, v91
	v_fmac_f32_e32 v89, v48, v90
	v_fmac_f32_e32 v88, v60, v94
	v_add_f32_e32 v97, v97, v98
	v_fmac_f32_e32 v89, v49, v91
	v_fmac_f32_e32 v88, v61, v95
	v_add_f32_e32 v100, v96, v89
	v_add_f32_e32 v111, v97, v88
	v_mul_f32_e32 v93, v59, v93
	ds_read_b128 v[88:91], v74 offset:62464
	ds_read_b128 v[96:99], v74 offset:61440
	v_fmac_f32_e32 v93, v58, v92
	v_fmac_f32_e32 v93, v56, v94
	v_fmac_f32_e32 v93, v57, v95
	v_add_f32_e32 v112, v100, v93
	ds_read_b128 v[92:95], v74 offset:64512
	ds_read_b128 v[100:103], v74 offset:63488
	s_waitcnt lgkmcnt(2)
	v_mul_f32_e32 v7, v7, v97
	v_fmac_f32_e32 v7, v6, v96
	v_mul_f32_e32 v43, v43, v97
	v_fmac_f32_e32 v7, v2, v98
	v_mul_f32_e32 v6, v9, v89
	v_fmac_f32_e32 v43, v42, v96
	v_fmac_f32_e32 v7, v3, v99
	v_mul_f32_e32 v3, v47, v89
	v_fmac_f32_e32 v6, v8, v88
	v_fmac_f32_e32 v43, v40, v98
	v_fmac_f32_e32 v3, v46, v88
	v_fmac_f32_e32 v6, v4, v90
	s_waitcnt lgkmcnt(0)
	v_mul_f32_e32 v4, v55, v101
	v_fmac_f32_e32 v43, v41, v99
	v_fmac_f32_e32 v3, v44, v90
	v_fmac_f32_e32 v4, v54, v100
	v_add_f32_e32 v40, 0, v43
	v_fmac_f32_e32 v3, v45, v91
	v_fmac_f32_e32 v4, v52, v102
	v_add_f32_e32 v3, v3, v40
	v_fmac_f32_e32 v4, v53, v103
	v_add_f32_e32 v3, v4, v3
	v_mul_f32_e32 v4, v51, v101
	v_fmac_f32_e32 v4, v50, v100
	v_add_f32_e32 v2, 0, v7
	v_fmac_f32_e32 v6, v5, v91
	v_fmac_f32_e32 v4, v48, v102
	v_add_f32_e32 v2, v6, v2
	v_fmac_f32_e32 v4, v49, v103
	v_add_f32_e32 v2, v4, v2
	v_mul_f32_e32 v4, v63, v93
	v_fmac_f32_e32 v4, v62, v92
	v_fmac_f32_e32 v4, v60, v94
	v_fmac_f32_e32 v4, v61, v95
	v_add_f32_e32 v3, v4, v3
	v_mul_f32_e32 v4, v59, v93
	v_fmac_f32_e32 v4, v58, v92
	v_fmac_f32_e32 v4, v56, v94
	v_fmac_f32_e32 v4, v57, v95
	v_add_f32_e32 v2, v4, v2
	v_cndmask_b32_e64 v4, v12, v64, s[0:1]
	ds_bpermute_b32 v4, v1, v4
	v_cndmask_b32_e64 v5, v64, v12, s[0:1]
	v_cndmask_b32_e64 v7, v11, v39, s[0:1]
	ds_bpermute_b32 v7, v1, v7
	v_cndmask_b32_e64 v8, v67, v68, s[0:1]
	s_waitcnt lgkmcnt(1)
	v_add_f32_e32 v4, v5, v4
	v_cndmask_b32_e64 v5, v65, v66, s[0:1]
	ds_bpermute_b32 v5, v1, v5
	ds_bpermute_b32 v8, v1, v8
	v_cndmask_b32_e64 v9, v69, v76, s[0:1]
	v_cndmask_b32_e64 v6, v39, v11, s[0:1]
	ds_bpermute_b32 v9, v1, v9
	v_cndmask_b32_e64 v11, v77, v78, s[0:1]
	ds_bpermute_b32 v11, v1, v11
	v_cndmask_b32_e64 v12, v79, v80, s[0:1]
	s_waitcnt lgkmcnt(4)
	v_add_f32_e32 v6, v6, v7
	v_cndmask_b32_e64 v7, v66, v65, s[0:1]
	ds_bpermute_b32 v12, v1, v12
	v_cndmask_b32_e64 v39, v81, v82, s[0:1]
	s_waitcnt lgkmcnt(4)
	v_add_f32_e32 v5, v7, v5
	v_cndmask_b32_e64 v7, v68, v67, s[0:1]
	ds_bpermute_b32 v39, v1, v39
	v_cndmask_b32_e64 v40, v83, v84, s[0:1]
	s_waitcnt lgkmcnt(4)
	v_add_f32_e32 v7, v7, v8
	v_cndmask_b32_e64 v8, v76, v69, s[0:1]
	ds_bpermute_b32 v40, v1, v40
	v_cndmask_b32_e64 v41, v85, v86, s[0:1]
	s_waitcnt lgkmcnt(4)
	v_add_f32_e32 v8, v8, v9
	v_cndmask_b32_e64 v9, v78, v77, s[0:1]
	ds_bpermute_b32 v41, v1, v41
	s_waitcnt lgkmcnt(4)
	v_add_f32_e32 v9, v9, v11
	v_cndmask_b32_e64 v11, v80, v79, s[0:1]
	s_waitcnt lgkmcnt(3)
	v_add_f32_e32 v11, v11, v12
	v_cndmask_b32_e64 v12, v82, v81, s[0:1]
	s_waitcnt lgkmcnt(2)
	v_add_f32_e32 v12, v12, v39
	v_cndmask_b32_e64 v39, v84, v83, s[0:1]
	v_cndmask_b32_e64 v42, v87, v104, s[0:1]
	s_waitcnt lgkmcnt(1)
	v_add_f32_e32 v39, v39, v40
	v_cndmask_b32_e64 v40, v86, v85, s[0:1]
	ds_bpermute_b32 v42, v1, v42
	v_cndmask_b32_e64 v43, v105, v106, s[0:1]
	s_waitcnt lgkmcnt(1)
	v_add_f32_e32 v40, v40, v41
	ds_bpermute_b32 v43, v1, v43
	v_cndmask_b32_e64 v44, v107, v108, s[0:1]
	v_cndmask_b32_e64 v47, v3, v2, s[0:1]
	v_cndmask_b32_e64 v2, v2, v3, s[0:1]
	v_cndmask_b32_e64 v3, v39, v4, s[6:7]
	v_cndmask_b32_e64 v4, v4, v39, s[6:7]
	ds_bpermute_b32 v44, v1, v44
	ds_bpermute_b32 v4, v37, v4
	v_cndmask_b32_e64 v39, v6, v40, s[6:7]
	ds_bpermute_b32 v39, v37, v39
	v_cndmask_b32_e64 v41, v104, v87, s[0:1]
	s_waitcnt lgkmcnt(4)
	v_add_f32_e32 v41, v41, v42
	v_cndmask_b32_e64 v42, v106, v105, s[0:1]
	s_waitcnt lgkmcnt(3)
	v_add_f32_e32 v42, v42, v43
	v_cndmask_b32_e64 v43, v108, v107, s[0:1]
	v_cndmask_b32_e64 v45, v109, v110, s[0:1]
	s_waitcnt lgkmcnt(2)
	v_add_f32_e32 v43, v43, v44
	ds_bpermute_b32 v45, v1, v45
	v_cndmask_b32_e64 v46, v111, v112, s[0:1]
	s_waitcnt lgkmcnt(2)
	v_add_f32_e32 v3, v3, v4
	v_cndmask_b32_e64 v4, v40, v6, s[6:7]
	v_cndmask_b32_e64 v6, v42, v7, s[6:7]
	v_cndmask_b32_e64 v7, v7, v42, s[6:7]
	ds_bpermute_b32 v46, v1, v46
	ds_bpermute_b32 v47, v1, v47
	s_waitcnt lgkmcnt(3)
	v_add_f32_e32 v4, v4, v39
	ds_bpermute_b32 v7, v37, v7
	v_cndmask_b32_e64 v39, v8, v43, s[6:7]
	ds_bpermute_b32 v39, v37, v39
	v_cndmask_b32_e64 v44, v110, v109, s[0:1]
	s_waitcnt lgkmcnt(4)
	v_add_f32_e32 v44, v44, v45
	v_cndmask_b32_e64 v45, v112, v111, s[0:1]
	s_waitcnt lgkmcnt(3)
	v_add_f32_e32 v45, v45, v46
	s_waitcnt lgkmcnt(2)
	v_add_f32_e32 v2, v2, v47
	s_waitcnt lgkmcnt(1)
	v_add_f32_e32 v6, v6, v7
	v_cndmask_b32_e64 v7, v43, v8, s[6:7]
	v_cndmask_b32_e64 v46, v5, v41, s[6:7]
	v_cndmask_b32_e64 v40, v9, v44, s[6:7]
	s_waitcnt lgkmcnt(0)
	v_add_f32_e32 v7, v7, v39
	v_cndmask_b32_e64 v8, v44, v9, s[6:7]
	v_cndmask_b32_e64 v9, v45, v11, s[6:7]
	v_cndmask_b32_e64 v11, v11, v45, s[6:7]
	v_cndmask_b32_e64 v39, v12, v2, s[6:7]
	ds_bpermute_b32 v46, v37, v46
	ds_bpermute_b32 v40, v37, v40
	ds_bpermute_b32 v11, v37, v11
	ds_bpermute_b32 v39, v37, v39
	v_cndmask_b32_e64 v5, v41, v5, s[6:7]
	v_cndmask_b32_e64 v2, v2, v12, s[6:7]
	s_waitcnt lgkmcnt(3)
	v_add_f32_e32 v5, v5, v46
	s_waitcnt lgkmcnt(2)
	v_add_f32_e32 v8, v8, v40
	s_waitcnt lgkmcnt(1)
	v_add_f32_e32 v9, v9, v11
	s_waitcnt lgkmcnt(0)
	v_add_f32_e32 v2, v2, v39
	v_cndmask_b32_e64 v40, v3, v7, s[8:9]
	v_cndmask_b32_e64 v3, v7, v3, s[8:9]
	v_cndmask_b32_e64 v7, v8, v4, s[8:9]
	v_cndmask_b32_e64 v4, v4, v8, s[8:9]
	v_cndmask_b32_e64 v8, v5, v9, s[8:9]
	v_cndmask_b32_e64 v11, v6, v2, s[8:9]
	ds_bpermute_b32 v40, v70, v40
	ds_bpermute_b32 v4, v70, v4
	ds_bpermute_b32 v8, v70, v8
	ds_bpermute_b32 v11, v70, v11
	v_cndmask_b32_e64 v5, v9, v5, s[8:9]
	v_cndmask_b32_e64 v2, v2, v6, s[8:9]
	s_waitcnt lgkmcnt(3)
	v_add_f32_e32 v3, v3, v40
	s_waitcnt lgkmcnt(2)
	v_add_f32_e32 v4, v7, v4
	s_waitcnt lgkmcnt(1)
	v_add_f32_e32 v5, v5, v8
	s_waitcnt lgkmcnt(0)
	v_add_f32_e32 v2, v2, v11
	v_cndmask_b32_e64 v6, v3, v5, s[10:11]
	v_cndmask_b32_e64 v7, v4, v2, s[10:11]
	ds_bpermute_b32 v6, v71, v6
	ds_bpermute_b32 v7, v71, v7
	v_cndmask_b32_e64 v3, v5, v3, s[10:11]
	v_cndmask_b32_e64 v2, v2, v4, s[10:11]
	s_waitcnt lgkmcnt(1)
	v_add_f32_e32 v3, v3, v6
	s_waitcnt lgkmcnt(0)
	v_add_f32_e32 v2, v2, v7
	v_cndmask_b32_e64 v4, v3, v2, s[12:13]
	ds_bpermute_b32 v4, v72, v4
	v_cndmask_b32_e64 v2, v2, v3, s[12:13]
	s_waitcnt lgkmcnt(0)
	v_add_f32_e32 v2, v2, v4
	ds_bpermute_b32 v3, v73, v2
	s_waitcnt lgkmcnt(0)
	v_add_f32_e32 v2, v2, v3
	ds_bpermute_b32 v3, v72, v2
	s_waitcnt lgkmcnt(0)
	v_max_f32_e32 v3, v3, v3
	v_max_f32_e32 v3, v2, v3
	ds_bpermute_b32 v4, v71, v3
	s_waitcnt lgkmcnt(0)
	v_max_f32_e32 v4, v4, v4
	v_max_f32_e32 v3, v3, v4
	ds_bpermute_b32 v4, v70, v3
	s_waitcnt lgkmcnt(0)
	v_max_f32_e32 v4, v4, v4
	v_max_f32_e32 v3, v3, v4
	ds_bpermute_b32 v4, v37, v3
	s_waitcnt lgkmcnt(0)
	v_max_f32_e32 v4, v4, v4
	v_max_f32_e32 v3, v3, v4
	v_sub_f32_e32 v2, v2, v3
	v_mul_f32_e32 v2, 0x3fb8aa3b, v2
	v_exp_f32_e32 v2, v2
	ds_bpermute_b32 v3, v72, v2
	s_waitcnt lgkmcnt(0)
	v_add_f32_e32 v3, v2, v3
	ds_bpermute_b32 v4, v71, v3
	s_waitcnt lgkmcnt(0)
	v_add_f32_e32 v3, v3, v4
	ds_bpermute_b32 v4, v70, v3
	s_waitcnt lgkmcnt(0)
	v_add_f32_e32 v3, v3, v4
	ds_bpermute_b32 v4, v37, v3
	s_and_saveexec_b64 s[4:5], s[14:15]
	s_cbranch_execz .LBB0_1229
	s_waitcnt lgkmcnt(0)
	v_add_f32_e32 v3, v3, v4
	v_div_scale_f32 v4, s[30:31], v3, v3, v2
	v_rcp_f32_e32 v5, v4
	v_ashrrev_i32_e32 v39, 31, v38
	v_and_or_b32 v6, v10, s27, v75
	v_lshlrev_b32_e32 v12, 2, v6
	v_fma_f32 v7, -v4, v5, 1.0
	v_fmac_f32_e32 v5, v7, v5
	v_div_scale_f32 v7, vcc, v2, v3, v2
	v_mul_f32_e32 v8, v7, v5
	v_fma_f32 v9, -v4, v8, v7
	v_fmac_f32_e32 v8, v9, v5
	v_fma_f32 v4, -v4, v8, v7
	v_div_fmas_f32 v4, v4, v5, v8
	v_div_fixup_f32 v4, v4, v3, v2
	v_lshlrev_b64 v[2:3], 18, v[38:39]
	v_lshl_add_u64 v[2:3], v[24:25], 0, v[2:3]
	v_lshl_add_u64 v[2:3], v[2:3], 0, v[12:13]
	global_store_dword v[2:3], v4, off sc1
	s_branch .LBB0_1229

.LBB0_1269:
	s_andn2_saveexec_b64 s[4:5], s[4:5]
	s_cbranch_execz .LBB0_1289
	s_mov_b64 s[4:5], exec
	s_nop 0
	s_waitcnt lgkmcnt(0)
	s_waitcnt vmcnt(0)
	v_mbcnt_lo_u32_b32 v2, s4, 0
	v_mbcnt_hi_u32_b32 v2, s5, v2
	v_cmp_eq_u32_e32 vcc, 0, v2
	s_and_saveexec_b64 s[6:7], vcc
	s_cbranch_execz .LBB0_1272
	s_bcnt1_i32_b64 s4, s[4:5]
	v_mov_b32_e32 v3, 0x3000
	v_mov_b32_e32 v4, s4
	global_atomic_add v3, v3, v4, s[92:93] offset:1024 sc0
